# K^T chunk scratch stored in 16-byte-unit layout so prep-phase stores and state-MFMA loads are coalesced (was one 16B access per 128B row); plus XCD-local barriers
# speedup vs baseline: 1.2094x; 1.0196x over previous
.LBB0_237:
	s_mul_hi_i32 s0, s2, 0x2aaaaaab
	s_lshr_b32 s1, s0, 31
	s_ashr_i32 s0, s0, 2
	s_add_i32 s0, s0, s1
	s_add_i32 s4, s0, s24
	v_mov_b32_e32 v48, v207
	s_lshl_b32 s5, s4, 8
	s_mul_i32 s0, s0, 24
	v_ashrrev_i32_e32 v49, 3, v48
	v_add_u32_e32 v0, s5, v49
	s_waitcnt lgkmcnt(0)
	v_ashrrev_i32_e32 v1, 31, v0
	v_lshlrev_b64 v[0:1], 11, v[0:1]
	v_lshlrev_b32_e32 v4, 4, v48
	v_and_b32_e32 v160, 0x70, v4
	v_lshl_add_u64 v[0:1], s[6:7], 0, v[0:1]
	v_lshl_add_u64 v[130:131], v[0:1], 0, v[160:161]
	v_add_co_u32_e32 v0, vcc, s33, v130
	s_sub_i32 s0, s2, s0
	s_nop 0
	v_addc_co_u32_e32 v1, vcc, 0, v131, vcc
	v_add_co_u32_e32 v4, vcc, s37, v130
	s_and_b32 s1, s4, 1
	s_lshl_b32 s1, s1, 2
	s_add_i32 s0, s0, s1
	s_add_i32 s1, s0, -24
	s_cmpk_ge_i32 s0, 24
	s_cselect_b32 s0, s1, s0
	s_lshl_b32 s40, s0, 7
	s_nop 0
	v_addc_co_u32_e32 v5, vcc, 0, v131, vcc
	v_add_co_u32_e32 v8, vcc, s39, v130
	v_add_u32_e32 v2, s40, v49
	s_nop 0
	v_addc_co_u32_e32 v9, vcc, 0, v131, vcc
	v_add_co_u32_e32 v12, vcc, s66, v130
	v_ashrrev_i32_e32 v3, 31, v2
	s_nop 0
	v_addc_co_u32_e32 v13, vcc, 0, v131, vcc
	v_add_co_u32_e32 v16, vcc, s67, v130
	v_lshlrev_b64 v[2:3], 11, v[2:3]
	s_nop 0
	v_addc_co_u32_e32 v17, vcc, 0, v131, vcc
	v_add_co_u32_e32 v20, vcc, s68, v130
	v_lshl_add_u64 v[2:3], s[58:59], 0, v[2:3]
	s_nop 0
	v_addc_co_u32_e32 v21, vcc, 0, v131, vcc
	v_add_co_u32_e32 v32, vcc, s69, v130
	v_lshl_add_u64 v[128:129], v[2:3], 0, v[160:161]
	s_nop 0
	v_addc_co_u32_e32 v33, vcc, 0, v131, vcc
	v_add_co_u32_e32 v36, vcc, s33, v128
	global_load_dwordx4 v[0:3], v[0:1], off
	s_nop 0
	global_load_dwordx4 v[4:7], v[4:5], off
	v_addc_co_u32_e32 v37, vcc, 0, v129, vcc
	v_add_co_u32_e32 v40, vcc, s37, v128
	global_load_dwordx4 v[8:11], v[8:9], off
	s_nop 0
	global_load_dwordx4 v[12:15], v[12:13], off
	v_addc_co_u32_e32 v41, vcc, 0, v129, vcc
	v_add_co_u32_e32 v44, vcc, s39, v128
	global_load_dwordx4 v[16:19], v[16:17], off
	s_nop 0
	global_load_dwordx4 v[20:23], v[20:21], off
	v_addc_co_u32_e32 v45, vcc, 0, v129, vcc
	global_load_dwordx4 v[24:27], v[130:131], off
	global_load_dwordx4 v[28:31], v[128:129], off
	s_nop 0
	global_load_dwordx4 v[32:35], v[32:33], off
	s_nop 0
	global_load_dwordx4 v[36:39], v[36:37], off
	s_nop 0
	global_load_dwordx4 v[40:43], v[40:41], off
	s_nop 0
	global_load_dwordx4 v[44:47], v[44:45], off
	v_lshrrev_b32_e32 v50, 5, v48
	v_ashrrev_i32_e32 v51, 4, v48
	v_xor_b32_e32 v53, v50, v48
	v_lshlrev_b32_e32 v54, 12, v49
	v_xor_b32_e32 v52, v51, v48
	v_lshlrev_b32_e32 v53, 4, v53
	v_and_b32_e32 v54, 0x1000, v54
	v_lshlrev_b32_e32 v52, 4, v52
	v_and_b32_e32 v53, 0x70, v53
	v_lshl_add_u32 v51, v51, 7, v54
	v_and_b32_e32 v52, 0x70, v52
	v_lshlrev_b32_e32 v49, 7, v49
	v_or_b32_e32 v54, v51, v53
	v_bfe_u32 v187, v48, 5, 1
	v_bfe_u32 v132, v48, 6, 1
	v_ashrrev_i32_e32 v133, 7, v48
	v_and_b32_e32 v188, 31, v48
	v_add_u32_e32 v142, v51, v53
	v_add_u32_e32 v143, v52, v49
	s_mov_b32 s41, 64
	v_mov_b32_e32 v96, 0
	v_mov_b32_e32 v97, v161
	v_mov_b32_e32 v98, v161
	v_mov_b32_e32 v99, v161
	v_mov_b32_e32 v100, v161
	v_mov_b32_e32 v101, v161
	v_mov_b32_e32 v102, v161
	v_mov_b32_e32 v103, v161
	v_mov_b32_e32 v104, v161
	v_mov_b32_e32 v105, v161
	v_mov_b32_e32 v106, v161
	v_mov_b32_e32 v107, v161
	v_mov_b32_e32 v108, v161
	v_mov_b32_e32 v109, v161
	v_mov_b32_e32 v110, v161
	s_waitcnt vmcnt(5)
	ds_write_b128 v54, v[24:27]
	ds_write_b128 v54, v[0:3] offset:2048
	ds_write_b128 v54, v[4:7] offset:8192
	ds_write_b128 v54, v[8:11] offset:10240
	ds_write_b128 v54, v[12:15] offset:16384
	ds_write_b128 v54, v[16:19] offset:18432
	ds_write_b128 v54, v[20:23] offset:24576
	s_waitcnt vmcnt(3)
	ds_write_b128 v54, v[32:35] offset:26624
	v_or_b32_e32 v0, v52, v49
	ds_write_b128 v0, v[28:31] offset:32768
	s_waitcnt vmcnt(2)
	ds_write_b128 v0, v[36:39] offset:36864
	s_waitcnt vmcnt(1)
	ds_write_b128 v0, v[40:43] offset:40960
	s_waitcnt vmcnt(0)
	ds_write_b128 v0, v[44:47] offset:45056
	v_bfe_u32 v0, v48, 1, 3
	v_bitop3_b32 v1, v50, v0, 1 bitop3:0x6c
	v_bitop3_b32 v6, v187, v0, 2 bitop3:0x36
	v_bitop3_b32 v8, v187, v0, 4 bitop3:0x36
	v_bitop3_b32 v0, v187, v0, 6 bitop3:0x36
	v_lshlrev_b32_e32 v1, 4, v1
	v_lshlrev_b32_e32 v2, 14, v132
	v_lshlrev_b32_e32 v5, 13, v133
	v_lshlrev_b32_e32 v6, 4, v6
	v_lshlrev_b32_e32 v8, 4, v8
	v_lshlrev_b32_e32 v0, 4, v0
	v_lshlrev_b32_e32 v3, 7, v188
	v_or_b32_e32 v4, v1, v2
	v_or_b32_e32 v1, v1, v5
	v_or_b32_e32 v7, v6, v2
	v_or_b32_e32 v6, v6, v5
	v_or_b32_e32 v9, v8, v2
	v_or_b32_e32 v8, v8, v5
	v_or_b32_e32 v2, v0, v2
	v_or_b32_e32 v0, v0, v5
	v_add_u32_e32 v134, v4, v3
	v_add_u32_e32 v135, v1, v3
	v_add_u32_e32 v136, v7, v3
	v_add_u32_e32 v137, v6, v3
	v_add_u32_e32 v138, v9, v3
	v_add_u32_e32 v139, v8, v3
	v_add_u32_e32 v140, v2, v3
	v_add_u32_e32 v141, v0, v3
	v_mov_b32_e32 v111, v161
	v_mov_b32_e32 v64, 0
	v_mov_b32_e32 v65, v161
	v_mov_b32_e32 v66, v161
	v_mov_b32_e32 v67, v161
	v_mov_b32_e32 v68, v161
	v_mov_b32_e32 v69, v161
	v_mov_b32_e32 v70, v161
	v_mov_b32_e32 v71, v161
	v_mov_b32_e32 v72, v161
	v_mov_b32_e32 v73, v161
	v_mov_b32_e32 v74, v161
	v_mov_b32_e32 v75, v161
	v_mov_b32_e32 v76, v161
	v_mov_b32_e32 v77, v161
	v_mov_b32_e32 v78, v161
	v_mov_b32_e32 v79, v161
	v_mov_b32_e32 v32, 0
	v_mov_b32_e32 v33, v161
	v_mov_b32_e32 v34, v161
	v_mov_b32_e32 v35, v161
	v_mov_b32_e32 v36, v161
	v_mov_b32_e32 v37, v161
	v_mov_b32_e32 v38, v161
	v_mov_b32_e32 v39, v161
	v_mov_b32_e32 v40, v161
	v_mov_b32_e32 v41, v161
	v_mov_b32_e32 v42, v161
	v_mov_b32_e32 v43, v161
	v_mov_b32_e32 v44, v161
	v_mov_b32_e32 v45, v161
	v_mov_b32_e32 v46, v161
	v_mov_b32_e32 v47, v161
	v_mov_b32_e32 v0, 0
	v_mov_b32_e32 v1, v161
	v_mov_b32_e32 v2, v161
	v_mov_b32_e32 v3, v161
	v_mov_b32_e32 v4, v161
	v_mov_b32_e32 v5, v161
	v_mov_b32_e32 v6, v161
	v_mov_b32_e32 v7, v161
	v_mov_b32_e32 v8, v161
	v_mov_b32_e32 v9, v161
	v_mov_b32_e32 v10, v161
	v_mov_b32_e32 v11, v161
	v_mov_b32_e32 v12, v161
	v_mov_b32_e32 v13, v161
	v_mov_b32_e32 v14, v161
	v_mov_b32_e32 v15, v161
	v_mov_b32_e32 v112, 0
	v_mov_b32_e32 v113, v161
	v_mov_b32_e32 v114, v161
	v_mov_b32_e32 v115, v161
	v_mov_b32_e32 v116, v161
	v_mov_b32_e32 v117, v161
	v_mov_b32_e32 v118, v161
	v_mov_b32_e32 v119, v161
	v_mov_b32_e32 v120, v161
	v_mov_b32_e32 v121, v161
	v_mov_b32_e32 v122, v161
	v_mov_b32_e32 v123, v161
	v_mov_b32_e32 v124, v161
	v_mov_b32_e32 v125, v161
	v_mov_b32_e32 v126, v161
	v_mov_b32_e32 v127, v161
	v_mov_b32_e32 v80, 0
	v_mov_b32_e32 v81, v161
	v_mov_b32_e32 v82, v161
	v_mov_b32_e32 v83, v161
	v_mov_b32_e32 v84, v161
	v_mov_b32_e32 v85, v161
	v_mov_b32_e32 v86, v161
	v_mov_b32_e32 v87, v161
	v_mov_b32_e32 v88, v161
	v_mov_b32_e32 v89, v161
	v_mov_b32_e32 v90, v161
	v_mov_b32_e32 v91, v161
	v_mov_b32_e32 v92, v161
	v_mov_b32_e32 v93, v161
	v_mov_b32_e32 v94, v161
	v_mov_b32_e32 v95, v161
	v_mov_b32_e32 v48, 0
	v_mov_b32_e32 v49, v161
	v_mov_b32_e32 v50, v161
	v_mov_b32_e32 v51, v161
	v_mov_b32_e32 v52, v161
	v_mov_b32_e32 v53, v161
	v_mov_b32_e32 v54, v161
	v_mov_b32_e32 v55, v161
	v_mov_b32_e32 v56, v161
	v_mov_b32_e32 v57, v161
	v_mov_b32_e32 v58, v161
	v_mov_b32_e32 v59, v161
	v_mov_b32_e32 v60, v161
	v_mov_b32_e32 v61, v161
	v_mov_b32_e32 v62, v161
	v_mov_b32_e32 v63, v161
	v_mov_b32_e32 v16, 0
	v_mov_b32_e32 v17, v161
	v_mov_b32_e32 v18, v161
	v_mov_b32_e32 v19, v161
	v_mov_b32_e32 v20, v161
	v_mov_b32_e32 v21, v161
	v_mov_b32_e32 v22, v161
	v_mov_b32_e32 v23, v161
	v_mov_b32_e32 v24, v161
	v_mov_b32_e32 v25, v161
	v_mov_b32_e32 v26, v161
	v_mov_b32_e32 v27, v161
	v_mov_b32_e32 v28, v161
	v_mov_b32_e32 v29, v161
	v_mov_b32_e32 v30, v161
	v_mov_b32_e32 v31, v161
	s_waitcnt lgkmcnt(0)
	s_barrier

.LBB0_407:
	s_cmp_lg_u32 s4, 0x18000
	s_cselect_b32 s36, s4, 0x12000
	v_lshl_add_u64 v[138:139], s[36:37], 1, v[72:73]
	v_add_co_u32_e32 v140, vcc, s92, v138
	s_nop 1
	v_addc_co_u32_e32 v141, vcc, 0, v139, vcc
	v_add_co_u32_e32 v142, vcc, s91, v138
	s_nop 1
	v_addc_co_u32_e32 v143, vcc, 0, v139, vcc
	s_add_i32 vcc_lo, s36, 0x2400
	s_mov_b32 vcc_hi, s37
	v_lshl_add_u64 v[144:145], vcc, 1, v[72:73]
	s_add_i32 vcc_lo, s36, 0x3000
	v_lshl_add_u64 v[146:147], vcc, 1, v[72:73]
	s_add_i32 vcc_lo, s36, 0x3c00
	v_lshl_add_u64 v[150:151], vcc, 1, v[72:73]
	s_add_i32 vcc_lo, s36, 0x4800
	v_lshl_add_u64 v[152:153], vcc, 1, v[72:73]
	s_addk_i32 s36, 0x5400
	global_load_dwordx2 v[138:139], v[138:139], off
	s_nop 0
	global_load_dwordx2 v[140:141], v[140:141], off offset:2048
	s_nop 0
	global_load_dwordx2 v[142:143], v[142:143], off
	s_nop 0
	global_load_dwordx2 v[144:145], v[144:145], off
	v_lshl_add_u64 v[174:175], s[36:37], 1, v[72:73]
	global_load_dwordx2 v[148:149], v[146:147], off
	s_nop 0
	global_load_dwordx2 v[150:151], v[150:151], off
	s_nop 0
	global_load_dwordx2 v[152:153], v[152:153], off
	s_nop 0
	global_load_dwordx2 v[146:147], v[174:175], off
	v_pk_mul_f32 v[174:175], v[98:99], v[164:165]
	v_pk_mul_f32 v[178:179], v[102:103], v[162:163]
	v_pk_mul_f32 v[184:185], v[80:81], v[168:169]
	v_pk_mul_f32 v[188:189], v[78:79], v[166:167]
	v_mov_b32_e32 v190, v174
	v_mov_b32_e32 v191, v178
	v_mov_b32_e32 v178, v175
	v_mov_b32_e32 v174, v184
	v_mov_b32_e32 v175, v188
	v_mov_b32_e32 v158, v165
	s_waitcnt vmcnt(15)
	v_lshlrev_b32_e32 v165, 16, v170
	v_mov_b32_e32 v160, v163
	v_and_b32_e32 v163, 0xffff0000, v170
	v_pk_add_f32 v[190:191], v[64:65], v[190:191]
	v_pk_add_f32 v[174:175], v[66:67], v[174:175]
	v_mov_b32_e32 v188, v185
	v_pk_mul_f32 v[184:185], v[98:99], v[158:159]
	v_mov_b32_e32 v158, v165
	v_pk_mul_f32 v[194:195], v[102:103], v[160:161]
	v_mov_b32_e32 v160, v163
	v_pk_add_f32 v[190:191], v[190:191], v[178:179]
	v_pk_add_f32 v[178:179], v[174:175], v[188:189]
	v_pk_mul_f32 v[188:189], v[108:109], v[158:159]
	v_pk_mul_f32 v[196:197], v[112:113], v[160:161]
	v_mov_b32_e32 v198, v189
	v_mov_b32_e32 v199, v197
	v_pk_add_f32 v[190:191], v[190:191], v[198:199]
	v_mov_b32_e32 v189, v196
	v_pk_add_f32 v[188:189], v[188:189], v[190:191]
	s_waitcnt vmcnt(14)
	v_lshlrev_b32_e32 v164, 16, v172
	v_mul_f32_e32 v154, 0xbfb8aa3b, v188
	v_exp_f32_e32 v154, v154
	v_and_b32_e32 v162, 0xffff0000, v172
	v_mov_b32_e32 v198, v184
	v_mov_b32_e32 v199, v194
	v_add_f32_e32 v154, 1.0, v154
	v_rcp_f32_e32 v190, v154
	v_mul_f32_e32 v154, 0xbfb8aa3b, v189
	v_exp_f32_e32 v154, v154
	v_pk_mul_f32 v[192:193], v[108:109], v[164:165]
	v_pk_add_f32 v[198:199], v[64:65], v[198:199]
	v_mov_b32_e32 v194, v185
	v_add_f32_e32 v154, 1.0, v154
	v_rcp_f32_e32 v191, v154
	v_pk_add_f32 v[184:185], v[198:199], v[194:195]
	v_mov_b32_e32 v194, v193
	v_mov_b32_e32 v156, v167
	v_pk_mul_f32 v[196:197], v[188:189], v[190:191]
	v_and_b32_e32 v199, 0xffff0000, v171
	v_pk_mul_f32 v[188:189], v[90:91], v[196:197]
	v_cvt_pk_bf16_f32 v166, v196, v197
	v_add_f32_e32 v154, 0, v188
	v_add_f32_e32 v202, v154, v189
	v_pk_mul_f32 v[188:189], v[92:93], v[196:197]
	v_pk_mul_f32 v[200:201], v[78:79], v[156:157]
	v_add_f32_e32 v154, 0, v188
	v_add_f32_e32 v203, v154, v189
	v_pk_fma_f32 v[188:189], v[24:25], v[196:197], 0 op_sel_hi:[1,0,0]
	v_mov_b32_e32 v156, v199
	v_pk_fma_f32 v[190:191], v[44:45], v[196:197], v[188:189] op_sel:[0,1,0]
	v_pk_mul_f32 v[188:189], v[82:83], v[196:197]
	v_lshlrev_b32_e32 v168, 16, v173
	v_add_f32_e32 v154, 0, v188
	v_add_f32_e32 v204, v154, v189
	v_pk_mul_f32 v[188:189], v[84:85], v[196:197]
	v_and_b32_e32 v198, 0xffff0000, v173
	v_add_f32_e32 v154, 0, v188
	v_add_f32_e32 v208, v154, v189
	v_pk_fma_f32 v[188:189], v[26:27], v[196:197], 0 op_sel_hi:[1,0,0]
	v_lshl_add_u64 v[174:175], s[58:59], 0, v[132:133]
	v_pk_fma_f32 v[188:189], v[46:47], v[196:197], v[188:189] op_sel:[0,1,0]
	v_pk_mul_f32 v[196:197], v[112:113], v[162:163]
	v_pk_mul_f32 v[158:159], v[100:101], v[158:159]
	v_mov_b32_e32 v195, v197
	v_pk_add_f32 v[184:185], v[194:195], v[184:185]
	v_mov_b32_e32 v193, v196
	v_pk_add_f32 v[184:185], v[192:193], v[184:185]
	v_pk_mul_f32 v[160:161], v[104:105], v[160:161]
	v_mul_f32_e32 v154, 0xbfb8aa3b, v184
	v_exp_f32_e32 v154, v154
	v_pk_mul_f32 v[210:211], v[104:105], v[162:163]
	s_waitcnt vmcnt(13)
	v_and_b32_e32 v220, 0xffff0000, v181
	s_waitcnt vmcnt(12)
	v_and_b32_e32 v221, 0xffff0000, v183
	v_add_f32_e32 v154, 1.0, v154
	v_rcp_f32_e32 v192, v154
	v_mul_f32_e32 v154, 0xbfb8aa3b, v185
	v_exp_f32_e32 v154, v154
	v_pk_mul_f32 v[214:215], v[62:63], v[198:199]
	s_mov_b32 s0, 0x9cd2000
	s_addk_i32 s4, 0x6000
	v_add_f32_e32 v154, 1.0, v154
	v_rcp_f32_e32 v193, v154
	v_mov_b32_e32 v154, v169
	v_lshlrev_b32_e32 v169, 16, v171
	v_pk_mul_f32 v[170:171], v[74:75], v[156:157]
	v_pk_mul_f32 v[184:185], v[184:185], v[192:193]
	v_pk_mul_f32 v[192:193], v[80:81], v[154:155]
	v_mov_b32_e32 v154, v169
	v_pk_mul_f32 v[194:195], v[76:77], v[154:155]
	v_mov_b32_e32 v173, v171
	v_mov_b32_e32 v172, v195
	v_pk_add_f32 v[172:173], v[178:179], v[172:173]
	v_mov_b32_e32 v195, v170
	v_pk_add_f32 v[170:171], v[194:195], v[172:173]
	v_pk_mul_f32 v[196:197], v[76:77], v[168:169]
	v_mul_f32_e32 v167, 0xbfb8aa3b, v170
	v_exp_f32_e32 v167, v167
	v_pk_mul_f32 v[154:155], v[2:3], v[154:155]
	v_pk_mul_f32 v[156:157], v[62:63], v[156:157]
	v_lshl_add_u64 v[132:133], v[132:133], 0, s[40:41]
	v_add_f32_e32 v167, 1.0, v167
	v_rcp_f32_e32 v172, v167
	v_mul_f32_e32 v167, 0xbfb8aa3b, v171
	v_exp_f32_e32 v167, v167
	s_cmp_eq_u32 s4, 0x1e000
	v_add_f32_e32 v167, 1.0, v167
	v_rcp_f32_e32 v173, v167
	s_nop 0
	v_pk_mul_f32 v[170:171], v[170:171], v[172:173]
	s_nop 0
	v_pk_mul_f32 v[172:173], v[94:95], v[170:171]
	v_pk_mul_f32 v[178:179], v[96:97], v[170:171]
	v_add_f32_e32 v167, v202, v172
	v_add_f32_e32 v167, v167, v173
	v_mul_f32_e32 v243, 0x3db504f3, v167
	v_add_f32_e32 v167, v203, v178
	v_add_f32_e32 v167, v167, v179
	v_pk_mul_f32 v[178:179], v[86:87], v[170:171]
	v_mul_f32_e32 v239, 0x3db504f3, v167
	v_add_f32_e32 v167, v204, v178
	v_pk_fma_f32 v[172:173], v[16:17], v[170:171], v[190:191] op_sel_hi:[1,0,1]
	v_add_f32_e32 v167, v167, v179
	v_pk_mul_f32 v[178:179], v[88:89], v[170:171]
	v_pk_fma_f32 v[188:189], v[18:19], v[170:171], v[188:189] op_sel_hi:[1,0,1]
	v_pk_fma_f32 v[172:173], v[28:29], v[170:171], v[172:173] op_sel:[0,1,0]
	v_mul_f32_e32 v237, 0x3db504f3, v167
	v_add_f32_e32 v167, v208, v178
	v_pk_fma_f32 v[188:189], v[30:31], v[170:171], v[188:189] op_sel:[0,1,0]
	v_add_co_u32_e32 v178, vcc, s96, v174
	v_add_f32_e32 v167, v167, v179
	v_cvt_pk_bf16_f32 v172, v172, v173
	v_cvt_pk_bf16_f32 v173, v188, v189
	v_addc_co_u32_e32 v179, vcc, 0, v175, vcc
	global_store_dwordx2 v[178:179], v[172:173], off
	v_add_co_u32_e32 v178, vcc, s97, v174
	v_mul_f32_e32 v204, 0x3db504f3, v167
	s_nop 0
	v_addc_co_u32_e32 v179, vcc, 0, v175, vcc
	v_cvt_pk_bf16_f32 v167, v170, v171
	v_add_co_u32_e32 v170, vcc, s33, v174
	v_cvt_pk_bf16_f32 v172, v243, v239
	s_nop 0
	v_addc_co_u32_e32 v171, vcc, 0, v175, vcc
	global_store_dwordx2 v[170:171], v[166:167], off
	v_mov_b32_e32 v170, v192
	v_mov_b32_e32 v171, v200
	v_cvt_pk_bf16_f32 v173, v237, v204
	v_pk_mul_f32 v[166:167], v[74:75], v[198:199]
	v_pk_add_f32 v[170:171], v[66:67], v[170:171]
	v_mov_b32_e32 v200, v193
	global_store_dwordx2 v[178:179], v[172:173], off
	v_pk_add_f32 v[170:171], v[170:171], v[200:201]
	v_mov_b32_e32 v172, v197
	v_mov_b32_e32 v173, v167
	v_pk_add_f32 v[170:171], v[172:173], v[170:171]
	v_mov_b32_e32 v197, v166
	v_pk_add_f32 v[166:167], v[196:197], v[170:171]
	v_pk_fma_f32 v[174:175], v[58:59], v[184:185], 0 op_sel_hi:[1,0,0]
	v_mul_f32_e32 v170, 0xbfb8aa3b, v166
	v_mul_f32_e32 v171, 0xbfb8aa3b, v167
	v_exp_f32_e32 v170, v170
	v_exp_f32_e32 v171, v171
	v_pk_fma_f32 v[174:175], v[50:51], v[184:185], v[174:175] op_sel:[0,1,0]
	v_add_f32_e32 v170, 1.0, v170
	v_add_f32_e32 v171, 1.0, v171
	v_rcp_f32_e32 v170, v170
	v_rcp_f32_e32 v171, v171
	s_nop 0
	v_pk_mul_f32 v[192:193], v[166:167], v[170:171]
	v_pk_fma_f32 v[166:167], v[120:121], v[164:165], 0 op_sel_hi:[1,1,0]
	v_pk_fma_f32 v[170:171], v[20:21], v[164:165], 0 op_sel_hi:[1,1,0]
	v_pk_fma_f32 v[166:167], v[118:119], v[162:163], v[166:167]
	v_pk_fma_f32 v[170:171], v[52:53], v[162:163], v[170:171]
	v_pk_fma_f32 v[166:167], v[116:117], v[168:169], v[166:167]
	v_pk_fma_f32 v[170:171], v[12:13], v[168:169], v[170:171]
	v_pk_fma_f32 v[188:189], v[114:115], v[198:199], v[166:167]
	v_pk_fma_f32 v[166:167], v[24:25], v[184:185], 0 op_sel_hi:[1,0,0]
	v_pk_fma_f32 v[178:179], v[36:37], v[198:199], v[170:171]
	v_pk_fma_f32 v[166:167], v[44:45], v[184:185], v[166:167] op_sel:[0,1,0]
	v_pk_fma_f32 v[170:171], v[56:57], v[184:185], 0 op_sel_hi:[1,0,0]
	v_pk_fma_f32 v[166:167], v[16:17], v[192:193], v[166:167] op_sel_hi:[1,0,1]
	v_pk_fma_f32 v[170:171], v[48:49], v[184:185], v[170:171] op_sel:[0,1,0]
	v_pk_fma_f32 v[166:167], v[28:29], v[192:193], v[166:167] op_sel:[0,1,0]
	v_pk_fma_f32 v[170:171], v[40:41], v[192:193], v[170:171] op_sel_hi:[1,0,1]
	v_cvt_pk_bf16_f32 v194, v166, v167
	v_lshl_add_u64 v[166:167], s[58:59], 0, v[130:131]
	v_pk_fma_f32 v[170:171], v[32:33], v[192:193], v[170:171] op_sel:[0,1,0]
	v_add_co_u32_e32 v200, vcc, s96, v166
	v_pk_mul_f32 v[190:191], v[170:171], s[38:39] op_sel_hi:[1,0]
	v_pk_fma_f32 v[170:171], v[128:129], v[164:165], 0 op_sel_hi:[1,1,0]
	v_addc_co_u32_e32 v201, vcc, 0, v167, vcc
	v_pk_fma_f32 v[170:171], v[126:127], v[162:163], v[170:171]
	v_add_co_u32_e32 v202, vcc, s97, v166
	v_pk_fma_f32 v[170:171], v[124:125], v[168:169], v[170:171]
	s_nop 0
	v_addc_co_u32_e32 v203, vcc, 0, v167, vcc
	v_pk_fma_f32 v[172:173], v[122:123], v[198:199], v[170:171]
	v_pk_fma_f32 v[170:171], v[26:27], v[184:185], 0 op_sel_hi:[1,0,0]
	v_add_co_u32_e32 v208, vcc, s33, v166
	v_pk_fma_f32 v[170:171], v[46:47], v[184:185], v[170:171] op_sel:[0,1,0]
	v_cvt_pk_bf16_f32 v184, v184, v185
	v_cvt_pk_bf16_f32 v185, v192, v193
	v_addc_co_u32_e32 v209, vcc, 0, v167, vcc
	global_store_dwordx2 v[208:209], v[184:185], off offset:1024
	v_mov_b32_e32 v184, v159
	v_mov_b32_e32 v185, v161
	v_pk_add_f32 v[184:185], v[64:65], v[184:185]
	v_mov_b32_e32 v159, v160
	v_pk_add_f32 v[160:161], v[158:159], v[184:185]
	v_mov_b32_e32 v158, v155
	v_mov_b32_e32 v159, v157
	v_pk_add_f32 v[158:159], v[66:67], v[158:159]
	v_mov_b32_e32 v155, v156
	v_pk_add_f32 v[158:159], v[154:155], v[158:159]
	v_lshlrev_b32_e32 v154, 16, v180
	v_mov_b32_e32 v156, v154
	v_mov_b32_e32 v157, v164
	v_pk_fma_f32 v[170:171], v[18:19], v[192:193], v[170:171] op_sel_hi:[1,0,1]
	v_pk_fma_f32 v[174:175], v[42:43], v[192:193], v[174:175] op_sel_hi:[1,0,1]
	v_pk_mul_f32 v[184:185], v[108:109], v[156:157]
	v_and_b32_e32 v156, 0xffff0000, v180
	v_pk_fma_f32 v[196:197], v[30:31], v[192:193], v[170:171] op_sel:[0,1,0]
	v_pk_fma_f32 v[174:175], v[34:35], v[192:193], v[174:175] op_sel:[0,1,0]
	v_mov_b32_e32 v192, v156
	v_mov_b32_e32 v193, v162
	v_pk_mul_f32 v[192:193], v[112:113], v[192:193]
	v_mov_b32_e32 v212, v185
	v_mov_b32_e32 v213, v193
	v_pk_add_f32 v[160:161], v[212:213], v[160:161]
	v_mov_b32_e32 v185, v192
	v_pk_fma_f32 v[170:171], v[22:23], v[164:165], 0 op_sel_hi:[1,1,0]
	v_pk_add_f32 v[160:161], v[184:185], v[160:161]
	v_pk_fma_f32 v[170:171], v[54:55], v[162:163], v[170:171]
	v_mul_f32_e32 v163, 0xbfb8aa3b, v160
	v_exp_f32_e32 v163, v163
	v_pk_mul_f32 v[174:175], v[174:175], s[38:39] op_sel_hi:[1,0]
	v_cvt_pk_bf16_f32 v195, v196, v197
	global_store_dwordx2 v[200:201], v[194:195], off offset:1024
	v_add_f32_e32 v163, 1.0, v163
	v_rcp_f32_e32 v184, v163
	v_mul_f32_e32 v163, 0xbfb8aa3b, v161
	v_exp_f32_e32 v163, v163
	v_cvt_pk_bf16_f32 v194, v190, v191
	v_cvt_pk_bf16_f32 v195, v174, v175
	global_store_dwordx2 v[202:203], v[194:195], off offset:1024
	v_add_f32_e32 v163, 1.0, v163
	v_rcp_f32_e32 v185, v163
	v_pk_mul_f32 v[194:195], v[100:101], v[164:165]
	v_lshlrev_b32_e32 v155, 16, v182
	v_and_b32_e32 v157, 0xffff0000, v182
	v_pk_mul_f32 v[160:161], v[160:161], v[184:185]
	v_mov_b32_e32 v212, v195
	v_pk_mul_f32 v[184:185], v[90:91], v[160:161]
	v_mov_b32_e32 v213, v211
	v_add_f32_e32 v163, 0, v184
	v_add_f32_e32 v163, v163, v185
	v_pk_mul_f32 v[184:185], v[92:93], v[160:161]
	v_pk_mul_f32 v[196:197], v[106:107], v[154:155]
	v_add_f32_e32 v165, 0, v184
	v_add_f32_e32 v165, v165, v185
	v_pk_fma_f32 v[184:185], v[24:25], v[160:161], 0 op_sel_hi:[1,0,0]
	v_pk_add_f32 v[212:213], v[64:65], v[212:213]
	v_pk_fma_f32 v[192:193], v[44:45], v[160:161], v[184:185] op_sel:[0,1,0]
	v_pk_mul_f32 v[184:185], v[82:83], v[160:161]
	v_mov_b32_e32 v195, v210
	v_add_f32_e32 v180, 0, v184
	v_add_f32_e32 v218, v180, v185
	v_pk_mul_f32 v[184:185], v[84:85], v[160:161]
	v_pk_add_f32 v[194:195], v[212:213], v[194:195]
	v_add_f32_e32 v180, 0, v184
	v_add_f32_e32 v219, v180, v185
	v_pk_fma_f32 v[184:185], v[26:27], v[160:161], 0 op_sel_hi:[1,0,0]
	v_cvt_pk_bf16_f32 v180, v160, v161
	v_pk_fma_f32 v[184:185], v[46:47], v[160:161], v[184:185] op_sel:[0,1,0]
	v_pk_mul_f32 v[160:161], v[110:111], v[156:157]
	v_mov_b32_e32 v210, v196
	v_mov_b32_e32 v211, v160
	v_pk_add_f32 v[194:195], v[194:195], v[210:211]
	v_mov_b32_e32 v160, v197
	v_pk_add_f32 v[160:161], v[194:195], v[160:161]
	v_lshlrev_b32_e32 v212, 16, v181
	v_mul_f32_e32 v182, 0xbfb8aa3b, v160
	v_exp_f32_e32 v182, v182
	v_lshlrev_b32_e32 v213, 16, v183
	v_mov_b32_e32 v196, v212
	v_mov_b32_e32 v197, v168
	v_add_f32_e32 v182, 1.0, v182
	v_rcp_f32_e32 v194, v182
	v_mul_f32_e32 v182, 0xbfb8aa3b, v161
	v_exp_f32_e32 v182, v182
	v_mov_b32_e32 v183, v198
	v_pk_mul_f32 v[196:197], v[76:77], v[196:197]
	v_pk_fma_f32 v[170:171], v[14:15], v[168:169], v[170:171]
	v_add_f32_e32 v182, 1.0, v182
	v_rcp_f32_e32 v195, v182
	v_mov_b32_e32 v182, v220
	v_pk_mul_f32 v[182:183], v[74:75], v[182:183]
	v_mov_b32_e32 v216, v197
	v_mov_b32_e32 v217, v183
	v_pk_add_f32 v[158:159], v[216:217], v[158:159]
	v_mov_b32_e32 v197, v182
	v_pk_add_f32 v[158:159], v[196:197], v[158:159]
	v_pk_mul_f32 v[160:161], v[160:161], v[194:195]
	v_pk_mul_f32 v[194:195], v[2:3], v[168:169]
	v_mul_f32_e32 v169, 0xbfb8aa3b, v158
	v_exp_f32_e32 v169, v169
	v_pk_mul_f32 v[210:211], v[6:7], v[212:213]
	v_pk_fma_f32 v[170:171], v[38:39], v[198:199], v[170:171]
	v_mov_b32_e32 v199, v220
	v_add_f32_e32 v169, 1.0, v169
	v_rcp_f32_e32 v182, v169
	v_mul_f32_e32 v169, 0xbfb8aa3b, v159
	v_exp_f32_e32 v169, v169
	v_pk_mul_f32 v[198:199], v[78:79], v[198:199]
	v_mov_b32_e32 v228, v157
	v_lshl_add_u64 v[130:131], v[130:131], 0, s[40:41]
	v_add_f32_e32 v169, 1.0, v169
	v_rcp_f32_e32 v183, v169
	v_mov_b32_e32 v169, v212
	v_pk_mul_f32 v[168:169], v[80:81], v[168:169]
	v_pk_mul_f32 v[158:159], v[158:159], v[182:183]
	s_nop 0
	v_pk_mul_f32 v[182:183], v[94:95], v[158:159]
	v_pk_fma_f32 v[184:185], v[18:19], v[158:159], v[184:185] op_sel_hi:[1,0,1]
	v_add_f32_e32 v163, v163, v182
	v_add_f32_e32 v163, v163, v183
	v_pk_fma_f32 v[182:183], v[16:17], v[158:159], v[192:193] op_sel_hi:[1,0,1]
	v_pk_mul_f32 v[192:193], v[96:97], v[158:159]
	v_mul_f32_e32 v246, 0x3db504f3, v163
	v_add_f32_e32 v163, v165, v192
	v_add_f32_e32 v163, v163, v193
	v_pk_mul_f32 v[192:193], v[86:87], v[158:159]
	v_mul_f32_e32 v242, 0x3db504f3, v163
	v_add_f32_e32 v163, v218, v192
	v_add_f32_e32 v163, v163, v193
	v_pk_mul_f32 v[192:193], v[88:89], v[158:159]
	v_mul_f32_e32 v241, 0x3db504f3, v163
	v_add_f32_e32 v163, v219, v192
	v_pk_fma_f32 v[182:183], v[28:29], v[158:159], v[182:183] op_sel:[0,1,0]
	v_pk_fma_f32 v[184:185], v[30:31], v[158:159], v[184:185] op_sel:[0,1,0]
	v_add_f32_e32 v163, v163, v193
	v_cvt_pk_bf16_f32 v181, v158, v159
	v_mul_f32_e32 v238, 0x3db504f3, v163
	v_cvt_pk_bf16_f32 v182, v182, v183
	v_cvt_pk_bf16_f32 v183, v184, v185
	global_store_dwordx2 v[208:209], v[180:181], off offset:2048
	v_mov_b32_e32 v180, v195
	v_mov_b32_e32 v181, v215
	global_store_dwordx2 v[200:201], v[182:183], off offset:2048
	v_cvt_pk_bf16_f32 v182, v246, v242
	v_cvt_pk_bf16_f32 v183, v241, v238
	v_pk_mul_f32 v[158:159], v[10:11], v[220:221]
	v_pk_add_f32 v[180:181], v[66:67], v[180:181]
	v_mov_b32_e32 v195, v214
	global_store_dwordx2 v[202:203], v[182:183], off offset:2048
	v_pk_add_f32 v[180:181], v[180:181], v[194:195]
	v_mov_b32_e32 v182, v210
	v_mov_b32_e32 v183, v158
	v_pk_add_f32 v[180:181], v[180:181], v[182:183]
	v_mov_b32_e32 v158, v211
	v_pk_add_f32 v[158:159], v[180:181], v[158:159]
	v_pk_fma_f32 v[184:185], v[58:59], v[160:161], 0 op_sel_hi:[1,0,0]
	v_mul_f32_e32 v163, 0xbfb8aa3b, v158
	v_exp_f32_e32 v163, v163
	v_pk_fma_f32 v[184:185], v[50:51], v[160:161], v[184:185] op_sel:[0,1,0]
	v_mov_b32_e32 v165, v154
	v_pk_mul_f32 v[164:165], v[98:99], v[164:165]
	v_add_f32_e32 v163, 1.0, v163
	v_rcp_f32_e32 v180, v163
	v_mul_f32_e32 v163, 0xbfb8aa3b, v159
	v_exp_f32_e32 v163, v163
	s_nop 0
	v_add_f32_e32 v163, 1.0, v163
	v_rcp_f32_e32 v181, v163
	v_mov_b32_e32 v163, v156
	v_pk_mul_f32 v[162:163], v[102:103], v[162:163]
	v_pk_mul_f32 v[158:159], v[158:159], v[180:181]
	v_pk_fma_f32 v[180:181], v[120:121], v[154:155], 0 op_sel_hi:[1,1,0]
	v_pk_fma_f32 v[184:185], v[42:43], v[158:159], v[184:185] op_sel_hi:[1,0,1]
	v_pk_fma_f32 v[180:181], v[118:119], v[156:157], v[180:181]
	v_pk_fma_f32 v[184:185], v[34:35], v[158:159], v[184:185] op_sel:[0,1,0]
	v_pk_fma_f32 v[180:181], v[116:117], v[212:213], v[180:181]
	v_pk_mul_f32 v[184:185], v[184:185], s[38:39] op_sel_hi:[1,0]
	v_pk_fma_f32 v[194:195], v[114:115], v[220:221], v[180:181]
	v_pk_fma_f32 v[180:181], v[24:25], v[160:161], 0 op_sel_hi:[1,0,0]
	s_nop 0
	v_pk_fma_f32 v[180:181], v[44:45], v[160:161], v[180:181] op_sel:[0,1,0]
	s_nop 0
	v_pk_fma_f32 v[180:181], v[16:17], v[158:159], v[180:181] op_sel_hi:[1,0,1]
	s_nop 0
	v_pk_fma_f32 v[210:211], v[28:29], v[158:159], v[180:181] op_sel:[0,1,0]
	v_pk_fma_f32 v[180:181], v[20:21], v[154:155], 0 op_sel_hi:[1,1,0]
	v_cvt_pk_bf16_f32 v210, v210, v211
	v_pk_fma_f32 v[180:181], v[52:53], v[156:157], v[180:181]
	s_nop 0
	v_pk_fma_f32 v[180:181], v[12:13], v[212:213], v[180:181]
	s_nop 0
	v_pk_fma_f32 v[192:193], v[36:37], v[220:221], v[180:181]
	v_pk_fma_f32 v[180:181], v[56:57], v[160:161], 0 op_sel_hi:[1,0,0]
	s_nop 0
	v_pk_fma_f32 v[180:181], v[48:49], v[160:161], v[180:181] op_sel:[0,1,0]
	s_nop 0
	v_pk_fma_f32 v[180:181], v[40:41], v[158:159], v[180:181] op_sel_hi:[1,0,1]
	s_nop 0
	v_pk_fma_f32 v[180:181], v[32:33], v[158:159], v[180:181] op_sel:[0,1,0]
	s_nop 0
	v_pk_mul_f32 v[196:197], v[180:181], s[38:39] op_sel_hi:[1,0]
	v_pk_fma_f32 v[180:181], v[128:129], v[154:155], 0 op_sel_hi:[1,1,0]
	s_nop 0
	v_pk_fma_f32 v[180:181], v[126:127], v[156:157], v[180:181]
	s_nop 0
	v_pk_fma_f32 v[180:181], v[124:125], v[212:213], v[180:181]
	s_nop 0
	v_pk_fma_f32 v[182:183], v[122:123], v[220:221], v[180:181]
	v_pk_fma_f32 v[180:181], v[26:27], v[160:161], 0 op_sel_hi:[1,0,0]
	s_nop 0
	v_pk_fma_f32 v[180:181], v[46:47], v[160:161], v[180:181] op_sel:[0,1,0]
	v_cvt_pk_bf16_f32 v160, v160, v161
	v_pk_fma_f32 v[180:181], v[18:19], v[158:159], v[180:181] op_sel_hi:[1,0,1]
	v_cvt_pk_bf16_f32 v161, v158, v159
	v_pk_fma_f32 v[214:215], v[30:31], v[158:159], v[180:181] op_sel:[0,1,0]
	global_store_dwordx2 v[208:209], v[160:161], off offset:3072
	v_mov_b32_e32 v208, v164
	v_mov_b32_e32 v209, v162
	v_cvt_pk_bf16_f32 v211, v214, v215
	v_pk_add_f32 v[208:209], v[64:65], v[208:209]
	v_mov_b32_e32 v162, v165
	global_store_dwordx2 v[200:201], v[210:211], off offset:3072
	v_cvt_pk_bf16_f32 v200, v196, v197
	v_cvt_pk_bf16_f32 v201, v184, v185
	s_waitcnt vmcnt(22)
	v_lshlrev_b32_e32 v161, 16, v187
	v_and_b32_e32 v159, 0xffff0000, v187
	v_mov_b32_e32 v160, v213
	v_mov_b32_e32 v158, v221
	v_pk_add_f32 v[218:219], v[208:209], v[162:163]
	v_mov_b32_e32 v162, v168
	v_mov_b32_e32 v163, v198
	global_store_dwordx2 v[202:203], v[200:201], off offset:3072
	v_pk_mul_f32 v[200:201], v[6:7], v[160:161]
	v_pk_mul_f32 v[202:203], v[10:11], v[158:159]
	v_pk_add_f32 v[162:163], v[66:67], v[162:163]
	v_mov_b32_e32 v198, v169
	v_pk_add_f32 v[162:163], v[162:163], v[198:199]
	v_mov_b32_e32 v164, v200
	v_mov_b32_e32 v165, v202
	v_pk_add_f32 v[162:163], v[162:163], v[164:165]
	v_mov_b32_e32 v202, v201
	v_pk_add_f32 v[162:163], v[162:163], v[202:203]
	v_pk_fma_f32 v[180:181], v[22:23], v[154:155], 0 op_sel_hi:[1,1,0]
	v_mul_f32_e32 v164, 0xbfb8aa3b, v162
	v_mul_f32_e32 v165, 0xbfb8aa3b, v163
	v_exp_f32_e32 v164, v164
	v_exp_f32_e32 v165, v165
	v_pk_fma_f32 v[180:181], v[54:55], v[156:157], v[180:181]
	v_and_b32_e32 v187, 0xffff0000, v186
	v_pk_fma_f32 v[180:181], v[14:15], v[212:213], v[180:181]
	v_pk_mul_f32 v[198:199], v[80:81], v[212:213]
	v_lshlrev_b32_e32 v212, 16, v186
	v_mov_b32_e32 v213, v187
	v_pk_fma_f32 v[180:181], v[38:39], v[220:221], v[180:181]
	v_add_f32_e32 v164, 1.0, v164
	v_add_f32_e32 v165, 1.0, v165
	v_pk_mul_f32 v[200:201], v[78:79], v[220:221]
	v_pk_mov_b32 v[220:221], v[154:155], v[212:213] op_sel:[1,0]
	v_mov_b32_e32 v229, v187
	v_rcp_f32_e32 v164, v164
	v_rcp_f32_e32 v165, v165
	v_pk_mul_f32 v[222:223], v[106:107], v[220:221]
	v_pk_mul_f32 v[224:225], v[110:111], v[228:229]
	v_mov_b32_e32 v226, v222
	v_mov_b32_e32 v227, v224
	v_pk_add_f32 v[218:219], v[218:219], v[226:227]
	v_mov_b32_e32 v224, v223
	v_pk_add_f32 v[218:219], v[218:219], v[224:225]
	v_pk_mul_f32 v[202:203], v[162:163], v[164:165]
	s_waitcnt vmcnt(22)
	v_lshlrev_b32_e32 v164, 16, v70
	v_and_b32_e32 v162, 0xffff0000, v70
	v_mul_f32_e32 v70, 0xbfb8aa3b, v218
	v_exp_f32_e32 v70, v70
	v_pk_mul_f32 v[216:217], v[94:95], v[202:203]
	s_waitcnt vmcnt(21)
	v_lshlrev_b32_e32 v165, 16, v176
	v_and_b32_e32 v163, 0xffff0000, v176
	v_add_f32_e32 v70, 1.0, v70
	v_rcp_f32_e32 v222, v70
	v_mul_f32_e32 v70, 0xbfb8aa3b, v219
	v_exp_f32_e32 v70, v70
	v_pk_mul_f32 v[214:215], v[96:97], v[202:203]
	v_pk_mul_f32 v[210:211], v[86:87], v[202:203]
	v_pk_mul_f32 v[208:209], v[88:89], v[202:203]
	v_add_f32_e32 v70, 1.0, v70
	v_rcp_f32_e32 v223, v70
	v_cvt_pk_bf16_f32 v169, v202, v203
	v_and_b32_e32 v186, 16, v186
	v_pk_mov_b32 v[250:251], v[186:187], v[162:163] op_sel:[1,0]
	v_pk_mul_f32 v[218:219], v[218:219], v[222:223]
	s_nop 0
	v_pk_mul_f32 v[222:223], v[90:91], v[218:219]
	v_pk_mul_f32 v[224:225], v[82:83], v[218:219]
	v_add_f32_e32 v70, 0, v222
	v_add_f32_e32 v70, v223, v70
	v_pk_mul_f32 v[222:223], v[92:93], v[218:219]
	v_add_f32_e32 v176, 0, v224
	v_add_f32_e32 v168, 0, v222
	v_add_f32_e32 v70, v216, v70
	v_add_f32_e32 v168, v223, v168
	v_pk_fma_f32 v[222:223], v[24:25], v[218:219], 0 op_sel_hi:[1,0,0]
	v_add_f32_e32 v176, v225, v176
	v_pk_mul_f32 v[224:225], v[84:85], v[218:219]
	v_add_f32_e32 v70, v217, v70
	v_pk_fma_f32 v[222:223], v[44:45], v[218:219], v[222:223] op_sel:[0,1,0]
	v_add_f32_e32 v224, 0, v224
	v_mul_f32_e32 v248, 0x3db504f3, v70
	v_add_f32_e32 v70, v214, v168
	v_add_f32_e32 v226, v225, v224
	v_pk_fma_f32 v[224:225], v[26:27], v[218:219], 0 op_sel_hi:[1,0,0]
	v_pk_fma_f32 v[216:217], v[16:17], v[202:203], v[222:223] op_sel_hi:[1,0,1]
	v_add_f32_e32 v70, v215, v70
	v_add_co_u32_e32 v222, vcc, s0, v166
	v_pk_fma_f32 v[224:225], v[46:47], v[218:219], v[224:225] op_sel:[0,1,0]
	v_mul_f32_e32 v245, 0x3db504f3, v70
	v_add_f32_e32 v70, v210, v176
	v_addc_co_u32_e32 v223, vcc, 0, v167, vcc
	s_mov_b32 s0, 0xacd2000
	v_add_f32_e32 v70, v211, v70
	v_pk_fma_f32 v[210:211], v[18:19], v[202:203], v[224:225] op_sel_hi:[1,0,1]
	v_add_co_u32_e32 v224, vcc, s0, v166
	s_mov_b32 s0, 0xccd2000
	s_nop 0
	v_addc_co_u32_e32 v225, vcc, 0, v167, vcc
	v_mul_f32_e32 v244, 0x3db504f3, v70
	v_add_f32_e32 v70, v208, v226
	v_add_co_u32_e32 v226, vcc, s0, v166
	v_mov_b32_e32 v166, v154
	s_nop 0
	v_addc_co_u32_e32 v227, vcc, 0, v167, vcc
	v_mov_b32_e32 v167, v156
	v_pk_fma_f32 v[166:167], v[60:61], v[166:167], v[64:65]
	v_mov_b32_e32 v156, v155
	v_pk_fma_f32 v[154:155], v[0:1], v[156:157], v[166:167]
	v_mov_b32_e32 v156, v164
	v_pk_fma_f32 v[154:155], v[4:5], v[212:213], v[154:155]
	v_mov_b32_e32 v157, v162
	v_add_f32_e32 v70, v209, v70
	v_pk_fma_f32 v[154:155], v[8:9], v[156:157], v[154:155]
	v_mul_f32_e32 v240, 0x3db504f3, v70
	v_mul_f32_e32 v70, 0xbfb8aa3b, v154
	v_exp_f32_e32 v70, v70
	v_pk_fma_f32 v[216:217], v[28:29], v[202:203], v[216:217] op_sel:[0,1,0]
	v_pk_fma_f32 v[202:203], v[30:31], v[202:203], v[210:211] op_sel:[0,1,0]
	v_cvt_pk_bf16_f32 v168, v218, v219
	v_add_f32_e32 v70, 1.0, v70
	v_rcp_f32_e32 v156, v70
	v_mul_f32_e32 v70, 0xbfb8aa3b, v155
	v_exp_f32_e32 v70, v70
	v_cvt_pk_bf16_f32 v209, v202, v203
	v_cvt_pk_bf16_f32 v202, v248, v245
	v_cvt_pk_bf16_f32 v203, v244, v240
	v_add_f32_e32 v70, 1.0, v70
	v_rcp_f32_e32 v157, v70
	global_store_dwordx2 v[226:227], v[168:169], off
	v_lshlrev_b32_e32 v169, 16, v177
	v_lshlrev_b32_e32 v168, 16, v71
	v_and_b32_e32 v167, 0xffff0000, v177
	v_and_b32_e32 v166, 0xffff0000, v71
	v_cvt_pk_bf16_f32 v208, v216, v217
	global_store_dwordx2 v[224:225], v[202:203], off
	v_pk_mul_f32 v[202:203], v[154:155], v[156:157]
	v_pk_mov_b32 v[154:155], v[168:169], v[168:169] op_sel:[1,0]
	v_pk_mov_b32 v[156:157], v[166:167], v[166:167] op_sel:[1,0]
	global_store_dwordx2 v[222:223], v[208:209], off
	v_mov_b32_e32 v208, v161
	v_mov_b32_e32 v209, v155
	v_mov_b32_e32 v218, v159
	v_mov_b32_e32 v219, v157
	v_mov_b32_e32 v214, v198
	v_mov_b32_e32 v215, v200
	v_pk_mul_f32 v[210:211], v[6:7], v[208:209]
	v_pk_mul_f32 v[176:177], v[10:11], v[218:219]
	v_pk_add_f32 v[214:215], v[66:67], v[214:215]
	v_mov_b32_e32 v200, v199
	v_pk_add_f32 v[198:199], v[214:215], v[200:201]
	v_mov_b32_e32 v200, v210
	v_mov_b32_e32 v201, v176
	v_pk_add_f32 v[198:199], v[198:199], v[200:201]
	v_mov_b32_e32 v176, v211
	v_pk_add_f32 v[176:177], v[198:199], v[176:177]
	v_mov_b32_e32 v213, v164
	v_mul_f32_e32 v71, 0xbfb8aa3b, v176
	v_exp_f32_e32 v71, v71
	v_cvt_pk_bf16_f32 v70, v202, v203
	v_pk_mul_f32 v[160:161], v[80:81], v[160:161]
	v_pk_mul_f32 v[158:159], v[78:79], v[158:159]
	v_add_f32_e32 v71, 1.0, v71
	v_rcp_f32_e32 v198, v71
	v_mul_f32_e32 v71, 0xbfb8aa3b, v177
	v_exp_f32_e32 v71, v71
	s_nop 0
	v_add_f32_e32 v71, 1.0, v71
	v_rcp_f32_e32 v199, v71
	s_nop 0
	v_pk_mul_f32 v[200:201], v[176:177], v[198:199]
	v_pk_fma_f32 v[176:177], v[120:121], v[212:213], 0 op_sel_hi:[1,1,0]
	v_pk_fma_f32 v[198:199], v[58:59], v[202:203], 0 op_sel_hi:[1,0,0]
	v_pk_fma_f32 v[176:177], v[118:119], v[250:251], v[176:177]
	v_pk_fma_f32 v[198:199], v[50:51], v[202:203], v[198:199] op_sel:[0,1,0]
	v_pk_fma_f32 v[176:177], v[116:117], v[208:209], v[176:177]
	v_pk_fma_f32 v[198:199], v[42:43], v[200:201], v[198:199] op_sel_hi:[1,0,1]
	v_pk_fma_f32 v[214:215], v[114:115], v[218:219], v[176:177]
	v_pk_fma_f32 v[176:177], v[24:25], v[202:203], 0 op_sel_hi:[1,0,0]
	v_pk_fma_f32 v[198:199], v[34:35], v[200:201], v[198:199] op_sel:[0,1,0]
	v_pk_fma_f32 v[176:177], v[44:45], v[202:203], v[176:177] op_sel:[0,1,0]
	v_pk_mul_f32 v[198:199], v[198:199], s[38:39] op_sel_hi:[1,0]
	v_pk_fma_f32 v[176:177], v[16:17], v[200:201], v[176:177] op_sel_hi:[1,0,1]
	v_cvt_pk_bf16_f32 v71, v200, v201
	v_pk_fma_f32 v[252:253], v[28:29], v[200:201], v[176:177] op_sel:[0,1,0]
	v_pk_fma_f32 v[176:177], v[20:21], v[212:213], 0 op_sel_hi:[1,1,0]
	global_store_dwordx2 v[226:227], v[70:71], off offset:1024
	v_pk_fma_f32 v[176:177], v[52:53], v[250:251], v[176:177]
	v_pk_mul_f32 v[70:71], v[98:99], v[220:221]
	v_pk_fma_f32 v[176:177], v[12:13], v[208:209], v[176:177]
	v_pk_mul_f32 v[220:221], v[110:111], v[162:163]
	v_pk_fma_f32 v[210:211], v[36:37], v[218:219], v[176:177]
	v_pk_fma_f32 v[176:177], v[56:57], v[202:203], 0 op_sel_hi:[1,0,0]
	s_nop 0
	v_pk_fma_f32 v[176:177], v[48:49], v[202:203], v[176:177] op_sel:[0,1,0]
	s_nop 0
	v_pk_fma_f32 v[176:177], v[40:41], v[200:201], v[176:177] op_sel_hi:[1,0,1]
	s_nop 0
	v_pk_fma_f32 v[176:177], v[32:33], v[200:201], v[176:177] op_sel:[0,1,0]
	s_nop 0
	v_pk_mul_f32 v[216:217], v[176:177], s[38:39] op_sel_hi:[1,0]
	v_pk_fma_f32 v[176:177], v[128:129], v[212:213], 0 op_sel_hi:[1,1,0]
	s_nop 0
	v_pk_fma_f32 v[176:177], v[126:127], v[250:251], v[176:177]
	s_nop 0
	v_pk_fma_f32 v[176:177], v[124:125], v[208:209], v[176:177]
	s_nop 0
	v_pk_fma_f32 v[186:187], v[122:123], v[218:219], v[176:177]
	v_pk_fma_f32 v[176:177], v[26:27], v[202:203], 0 op_sel_hi:[1,0,0]
	s_nop 0
	v_pk_fma_f32 v[176:177], v[46:47], v[202:203], v[176:177] op_sel:[0,1,0]
	v_cvt_pk_bf16_f32 v202, v252, v253
	v_pk_fma_f32 v[176:177], v[18:19], v[200:201], v[176:177] op_sel_hi:[1,0,1]
	v_mov_b32_e32 v252, v70
	v_pk_fma_f32 v[230:231], v[30:31], v[200:201], v[176:177] op_sel:[0,1,0]
	v_pk_mul_f32 v[200:201], v[106:107], v[164:165]
	v_cvt_pk_bf16_f32 v203, v230, v231
	global_store_dwordx2 v[222:223], v[202:203], off offset:1024
	v_cvt_pk_bf16_f32 v202, v216, v217
	v_cvt_pk_bf16_f32 v203, v198, v199
	global_store_dwordx2 v[224:225], v[202:203], off offset:1024
	v_pk_mul_f32 v[202:203], v[102:103], v[228:229]
	v_pk_mul_f32 v[228:229], v[6:7], v[168:169]
	v_mov_b32_e32 v253, v202
	v_pk_add_f32 v[252:253], v[64:65], v[252:253]
	v_mov_b32_e32 v202, v71
	v_pk_add_f32 v[70:71], v[252:253], v[202:203]
	v_mov_b32_e32 v202, v200
	v_mov_b32_e32 v203, v220
	v_pk_add_f32 v[70:71], v[70:71], v[202:203]
	v_mov_b32_e32 v220, v201
	v_pk_add_f32 v[70:71], v[70:71], v[220:221]
	v_mov_b32_e32 v220, v160
	v_mul_f32_e32 v155, 0xbfb8aa3b, v70
	v_exp_f32_e32 v155, v155
	v_mov_b32_e32 v221, v158
	v_pk_mul_f32 v[230:231], v[10:11], v[166:167]
	v_pk_add_f32 v[220:221], v[66:67], v[220:221]
	v_add_f32_e32 v155, 1.0, v155
	v_rcp_f32_e32 v200, v155
	v_mul_f32_e32 v155, 0xbfb8aa3b, v71
	v_mov_b32_e32 v158, v161
	v_exp_f32_e32 v155, v155
	v_pk_add_f32 v[158:159], v[220:221], v[158:159]
	v_mov_b32_e32 v160, v228
	v_mov_b32_e32 v161, v230
	v_pk_add_f32 v[158:159], v[158:159], v[160:161]
	v_mov_b32_e32 v230, v229
	v_pk_add_f32 v[158:159], v[158:159], v[230:231]
	v_add_f32_e32 v155, 1.0, v155
	v_mul_f32_e32 v160, 0xbfb8aa3b, v158
	v_mul_f32_e32 v161, 0xbfb8aa3b, v159
	v_exp_f32_e32 v160, v160
	v_exp_f32_e32 v161, v161
	v_rcp_f32_e32 v201, v155
	v_pk_fma_f32 v[176:177], v[22:23], v[212:213], 0 op_sel_hi:[1,1,0]
	v_add_f32_e32 v160, 1.0, v160
	v_add_f32_e32 v161, 1.0, v161
	v_pk_mul_f32 v[70:71], v[70:71], v[200:201]
	v_rcp_f32_e32 v160, v160
	v_rcp_f32_e32 v161, v161
	v_pk_mul_f32 v[200:201], v[90:91], v[70:71]
	v_pk_mul_f32 v[202:203], v[82:83], v[70:71]
	v_add_f32_e32 v155, 0, v200
	v_add_f32_e32 v155, v201, v155
	v_pk_mul_f32 v[200:201], v[92:93], v[70:71]
	v_pk_mul_f32 v[158:159], v[158:159], v[160:161]
	v_add_f32_e32 v157, 0, v200
	v_add_f32_e32 v157, v201, v157
	v_pk_fma_f32 v[200:201], v[24:25], v[70:71], 0 op_sel_hi:[1,0,0]
	v_pk_mul_f32 v[160:161], v[94:95], v[158:159]
	v_pk_fma_f32 v[200:201], v[44:45], v[70:71], v[200:201] op_sel:[0,1,0]
	v_add_f32_e32 v155, v160, v155
	v_add_f32_e32 v202, 0, v202
	v_add_f32_e32 v155, v161, v155
	v_pk_fma_f32 v[160:161], v[16:17], v[158:159], v[200:201] op_sel_hi:[1,0,1]
	v_pk_mul_f32 v[200:201], v[96:97], v[158:159]
	v_add_f32_e32 v252, v203, v202
	v_pk_mul_f32 v[202:203], v[84:85], v[70:71]
	v_mul_f32_e32 v249, 0x3db504f3, v155
	v_add_f32_e32 v155, v200, v157
	v_add_f32_e32 v202, 0, v202
	v_add_f32_e32 v155, v201, v155
	v_pk_mul_f32 v[200:201], v[86:87], v[158:159]
	v_add_f32_e32 v253, v203, v202
	v_pk_fma_f32 v[202:203], v[26:27], v[70:71], 0 op_sel_hi:[1,0,0]
	v_mul_f32_e32 v247, 0x3db504f3, v155
	v_add_f32_e32 v155, v200, v252
	v_pk_fma_f32 v[202:203], v[46:47], v[70:71], v[202:203] op_sel:[0,1,0]
	v_add_f32_e32 v155, v201, v155
	v_pk_mul_f32 v[200:201], v[88:89], v[158:159]
	v_mul_f32_e32 v229, 0x3db504f3, v155
	v_add_f32_e32 v155, v200, v253
	v_pk_fma_f32 v[202:203], v[18:19], v[158:159], v[202:203] op_sel_hi:[1,0,1]
	v_pk_fma_f32 v[160:161], v[28:29], v[158:159], v[160:161] op_sel:[0,1,0]
	v_pk_fma_f32 v[202:203], v[30:31], v[158:159], v[202:203] op_sel:[0,1,0]
	v_add_f32_e32 v155, v201, v155
	v_mul_f32_e32 v228, 0x3db504f3, v155
	v_cvt_pk_bf16_f32 v160, v160, v161
	v_cvt_pk_bf16_f32 v161, v202, v203
	global_store_dwordx2 v[222:223], v[160:161], off offset:2048
	v_cvt_pk_bf16_f32 v160, v249, v247
	v_cvt_pk_bf16_f32 v161, v229, v228
	global_store_dwordx2 v[224:225], v[160:161], off offset:2048
	v_cvt_pk_bf16_f32 v70, v70, v71
	v_cvt_pk_bf16_f32 v71, v158, v159
	s_waitcnt vmcnt(28)
	v_lshlrev_b32_e32 v159, 16, v68
	v_and_b32_e32 v161, 0xffff0000, v68
	v_lshlrev_b32_e32 v155, 16, v69
	v_and_b32_e32 v157, 0xffff0000, v69
	v_pk_mul_f32 v[68:69], v[98:99], v[212:213]
	v_pk_mul_f32 v[200:201], v[102:103], v[250:251]
	v_mov_b32_e32 v158, v165
	v_mov_b32_e32 v160, v163
	v_mov_b32_e32 v212, v68
	v_mov_b32_e32 v213, v200
	global_store_dwordx2 v[226:227], v[70:71], off offset:2048
	v_pk_mul_f32 v[70:71], v[106:107], v[158:159]
	v_pk_mul_f32 v[202:203], v[110:111], v[160:161]
	v_pk_add_f32 v[212:213], v[64:65], v[212:213]
	v_mov_b32_e32 v200, v69
	v_pk_add_f32 v[68:69], v[212:213], v[200:201]
	v_mov_b32_e32 v200, v70
	v_mov_b32_e32 v201, v202
	v_pk_add_f32 v[68:69], v[68:69], v[200:201]
	v_mov_b32_e32 v202, v71
	v_pk_add_f32 v[68:69], v[68:69], v[202:203]
	v_pk_mul_f32 v[202:203], v[78:79], v[218:219]
	v_mul_f32_e32 v70, 0xbfb8aa3b, v68
	v_mul_f32_e32 v71, 0xbfb8aa3b, v69
	v_exp_f32_e32 v70, v70
	v_exp_f32_e32 v71, v71
	v_pk_fma_f32 v[176:177], v[54:55], v[250:251], v[176:177]
	v_mov_b32_e32 v213, v202
	v_add_f32_e32 v70, 1.0, v70
	v_add_f32_e32 v71, 1.0, v71
	v_rcp_f32_e32 v70, v70
	v_rcp_f32_e32 v71, v71
	v_pk_fma_f32 v[176:177], v[14:15], v[208:209], v[176:177]
	v_pk_mul_f32 v[200:201], v[6:7], v[154:155]
	v_pk_fma_f32 v[176:177], v[38:39], v[218:219], v[176:177]
	v_pk_mul_f32 v[68:69], v[68:69], v[70:71]
	v_pk_mul_f32 v[70:71], v[80:81], v[208:209]
	v_pk_mul_f32 v[208:209], v[10:11], v[156:157]
	v_mov_b32_e32 v212, v70
	v_pk_add_f32 v[212:213], v[66:67], v[212:213]
	v_mov_b32_e32 v202, v71
	v_pk_add_f32 v[70:71], v[212:213], v[202:203]
	v_mov_b32_e32 v202, v200
	v_mov_b32_e32 v203, v208
	v_pk_add_f32 v[70:71], v[70:71], v[202:203]
	v_mov_b32_e32 v208, v201
	v_pk_add_f32 v[70:71], v[70:71], v[208:209]
	v_pk_fma_f32 v[208:209], v[58:59], v[68:69], 0 op_sel_hi:[1,0,0]
	v_mul_f32_e32 v200, 0xbfb8aa3b, v70
	v_mul_f32_e32 v201, 0xbfb8aa3b, v71
	v_exp_f32_e32 v200, v200
	v_exp_f32_e32 v201, v201
	v_pk_fma_f32 v[208:209], v[50:51], v[68:69], v[208:209] op_sel:[0,1,0]
	v_add_f32_e32 v200, 1.0, v200
	v_add_f32_e32 v201, 1.0, v201
	v_rcp_f32_e32 v200, v200
	v_rcp_f32_e32 v201, v201
	s_nop 0
	v_pk_mul_f32 v[70:71], v[70:71], v[200:201]
	v_pk_fma_f32 v[200:201], v[120:121], v[158:159], 0 op_sel_hi:[1,1,0]
	v_pk_fma_f32 v[208:209], v[42:43], v[70:71], v[208:209] op_sel_hi:[1,0,1]
	v_pk_fma_f32 v[200:201], v[118:119], v[160:161], v[200:201]
	v_pk_fma_f32 v[208:209], v[34:35], v[70:71], v[208:209] op_sel:[0,1,0]
	v_pk_fma_f32 v[200:201], v[116:117], v[154:155], v[200:201]
	v_pk_mul_f32 v[208:209], v[208:209], s[38:39] op_sel_hi:[1,0]
	v_pk_fma_f32 v[218:219], v[114:115], v[156:157], v[200:201]
	v_pk_fma_f32 v[200:201], v[24:25], v[68:69], 0 op_sel_hi:[1,0,0]
	s_nop 0
	v_pk_fma_f32 v[200:201], v[44:45], v[68:69], v[200:201] op_sel:[0,1,0]
	s_nop 0
	v_pk_fma_f32 v[200:201], v[16:17], v[70:71], v[200:201] op_sel_hi:[1,0,1]
	s_nop 0
	v_pk_fma_f32 v[230:231], v[28:29], v[70:71], v[200:201] op_sel:[0,1,0]
	v_pk_fma_f32 v[200:201], v[20:21], v[158:159], 0 op_sel_hi:[1,1,0]
	v_cvt_pk_bf16_f32 v230, v230, v231
	v_pk_fma_f32 v[200:201], v[52:53], v[160:161], v[200:201]
	s_nop 0
	v_pk_fma_f32 v[200:201], v[12:13], v[154:155], v[200:201]
	s_nop 0
	v_pk_fma_f32 v[212:213], v[36:37], v[156:157], v[200:201]
	v_pk_fma_f32 v[200:201], v[56:57], v[68:69], 0 op_sel_hi:[1,0,0]
	s_nop 0
	v_pk_fma_f32 v[200:201], v[48:49], v[68:69], v[200:201] op_sel:[0,1,0]
	s_nop 0
	v_pk_fma_f32 v[200:201], v[40:41], v[70:71], v[200:201] op_sel_hi:[1,0,1]
	s_nop 0
	v_pk_fma_f32 v[200:201], v[32:33], v[70:71], v[200:201] op_sel:[0,1,0]
	s_nop 0
	v_pk_mul_f32 v[220:221], v[200:201], s[38:39] op_sel_hi:[1,0]
	v_pk_fma_f32 v[200:201], v[128:129], v[158:159], 0 op_sel_hi:[1,1,0]
	s_nop 0
	v_pk_fma_f32 v[200:201], v[126:127], v[160:161], v[200:201]
	s_nop 0
	v_pk_fma_f32 v[200:201], v[124:125], v[154:155], v[200:201]
	s_nop 0
	v_pk_fma_f32 v[202:203], v[122:123], v[156:157], v[200:201]
	v_pk_fma_f32 v[200:201], v[26:27], v[68:69], 0 op_sel_hi:[1,0,0]
	s_nop 0
	v_pk_fma_f32 v[200:201], v[46:47], v[68:69], v[200:201] op_sel:[0,1,0]
	v_cvt_pk_bf16_f32 v68, v68, v69
	v_pk_fma_f32 v[200:201], v[18:19], v[70:71], v[200:201] op_sel_hi:[1,0,1]
	v_cvt_pk_bf16_f32 v69, v70, v71
	v_pk_fma_f32 v[250:251], v[30:31], v[70:71], v[200:201] op_sel:[0,1,0]
	global_store_dwordx2 v[226:227], v[68:69], off offset:3072
	v_cvt_pk_bf16_f32 v231, v250, v251
	global_store_dwordx2 v[222:223], v[230:231], off offset:3072
	v_cvt_pk_bf16_f32 v222, v220, v221
	v_cvt_pk_bf16_f32 v223, v208, v209
	global_store_dwordx2 v[224:225], v[222:223], off offset:3072
	v_lshl_add_u64 v[222:223], s[58:59], 0, v[136:137]
	v_and_b32_e32 v224, 0xffffc000, v134
	v_bfe_u32 v225, v134, 9, 5
	v_lshl_or_b32 v224, v225, 4, v224
	v_bfe_u32 v225, v134, 4, 3
	v_lshl_or_b32 v224, v225, 11, v224
	v_cvt_pk_bf16_f32 v68, v243, v190
	v_cvt_pk_bf16_f32 v69, v246, v196
	v_cvt_pk_bf16_f32 v70, v248, v216
	v_cvt_pk_bf16_f32 v71, v249, v220
	s_nop 0
	global_store_dwordx4 v224, v[68:71], s[84:85]
	v_pk_fma_f32 v[200:201], v[22:23], v[158:159], 0 op_sel_hi:[1,1,0]
	v_lshl_add_u64 v[136:137], v[136:137], 0, 16
	v_pk_mov_b32 v[68:69], v[188:189], v[188:189] op_sel:[1,0]
	v_add_co_u32_e32 v188, vcc, s75, v222
	v_cvt_pk_bf16_f32 v68, v68, v69
	v_cvt_pk_bf16_f32 v69, v194, v195
	v_cvt_pk_bf16_f32 v70, v214, v215
	v_cvt_pk_bf16_f32 v71, v218, v219
	v_addc_co_u32_e32 v189, vcc, 0, v223, vcc
	v_lshl_add_u64 v[194:195], s[58:59], 0, v[134:135]
	global_store_dwordx4 v[188:189], v[68:71], off
	v_add_co_u32_e32 v188, vcc, s74, v194
	s_nop 0
	v_cvt_pk_bf16_f32 v68, v239, v191
	v_cvt_pk_bf16_f32 v69, v242, v197
	v_cvt_pk_bf16_f32 v70, v245, v217
	v_cvt_pk_bf16_f32 v71, v247, v221
	v_addc_co_u32_e32 v189, vcc, 0, v195, vcc
	global_store_dwordx4 v224, v[68:71], s[84:85] offset:512
	v_pk_fma_f32 v[200:201], v[54:55], v[160:161], v[200:201]
	v_cvt_pk_bf16_f32 v191, v192, v193
	v_pk_mov_b32 v[68:69], v[178:179], v[178:179] op_sel:[1,0]
	v_cvt_pk_bf16_f32 v192, v210, v211
	v_cvt_pk_bf16_f32 v190, v68, v69
	v_add_co_u32_e32 v68, vcc, s75, v194
	v_cvt_pk_bf16_f32 v193, v212, v213
	s_nop 0
	v_addc_co_u32_e32 v69, vcc, 0, v195, vcc
	v_pk_fma_f32 v[200:201], v[14:15], v[154:155], v[200:201]
	global_store_dwordx4 v[68:69], v[190:193], off offset:128
	v_pk_mov_b32 v[70:71], v[172:173], v[172:173] op_sel:[1,0]
	v_pk_fma_f32 v[200:201], v[38:39], v[156:157], v[200:201]
	v_cvt_pk_bf16_f32 v190, v237, v174
	v_cvt_pk_bf16_f32 v191, v241, v184
	v_cvt_pk_bf16_f32 v192, v244, v198
	v_cvt_pk_bf16_f32 v193, v229, v208
	global_store_dwordx4 v224, v[190:193], s[84:85] offset:1024
	v_cvt_pk_bf16_f32 v172, v204, v175
	v_cvt_pk_bf16_f32 v173, v238, v185
	v_cvt_pk_bf16_f32 v190, v70, v71
	v_cvt_pk_bf16_f32 v174, v240, v199
	v_cvt_pk_bf16_f32 v175, v228, v209
	v_pk_mov_b32 v[70:71], v[170:171], v[170:171] op_sel:[1,0]
	v_cvt_pk_bf16_f32 v191, v182, v183
	v_cvt_pk_bf16_f32 v192, v186, v187
	v_cvt_pk_bf16_f32 v193, v202, v203
	global_store_dwordx4 v224, v[172:175], s[84:85] offset:1536
	v_cvt_pk_bf16_f32 v170, v70, v71
	v_cvt_pk_bf16_f32 v171, v180, v181
	v_cvt_pk_bf16_f32 v172, v176, v177
	v_cvt_pk_bf16_f32 v173, v200, v201
	global_store_dwordx4 v[68:69], v[190:193], off offset:256
	global_store_dwordx4 v[68:69], v[170:173], off offset:384
	v_lshl_add_u64 v[134:135], v[134:135], 0, 16
	s_waitcnt vmcnt(37)
	v_mov_b64_e32 v[180:181], v[142:143]
	v_mov_b64_e32 v[170:171], v[138:139]
	v_mov_b64_e32 v[172:173], v[140:141]
	s_waitcnt vmcnt(36)
	v_mov_b64_e32 v[182:183], v[144:145]
	s_waitcnt vmcnt(35)
	v_mov_b64_e32 v[186:187], v[148:149]
	s_waitcnt vmcnt(34)
	v_mov_b64_e32 v[70:71], v[150:151]
	s_waitcnt vmcnt(33)
	v_mov_b64_e32 v[176:177], v[152:153]
	s_waitcnt vmcnt(32)
	v_mov_b64_e32 v[68:69], v[146:147]
	s_cbranch_scc0 .LBB0_407
	s_ashr_i32 s68, s79, 6
	v_bfe_u32 v56, v236, 5, 1
	s_or_b32 s0, s69, s25
	s_lshl_b32 s4, s68, 8
	v_lshlrev_b32_e32 v54, 3, v56
	v_lshlrev_b32_e32 v204, 11, v206
	s_ashr_i32 s1, s0, 31
	v_or_b32_e32 v50, s4, v54
	v_lshl_add_u64 v[36:37], s[12:13], 0, v[204:205]
	v_or_b32_e32 v0, s0, v206
	v_mov_b32_e32 v1, s1
	v_mov_b64_e32 v[2:3], s[8:9]
	v_lshlrev_b32_e32 v204, 11, v206
	v_ashrrev_i32_e32 v51, 31, v50
	v_lshlrev_b64 v[38:39], 10, v[0:1]
	v_mad_i64_i32 v[42:43], vcc, v0, s93, v[2:3]
	v_lshl_add_u64 v[0:1], v[50:51], 1, v[204:205]
	v_or_b32_e32 v40, 0x8000, v38
	v_mov_b32_e32 v41, v39
	s_mov_b64 vcc, 0x30000
	v_lshl_add_u64 v[52:53], s[34:35], 0, v[0:1]
	v_mov_b32_e32 v0, 0
	v_and_b32_e32 v55, 63, v236
	v_lshl_add_u64 v[44:45], s[10:11], 0, v[38:39]
	v_lshl_add_u64 v[46:47], s[10:11], 0, v[40:41]
	v_lshl_add_u64 v[48:49], v[42:43], 0, vcc
	s_mov_b32 s5, 0
	v_mov_b32_e32 v1, v0
	v_mov_b32_e32 v2, v0
	v_mov_b32_e32 v3, v0
	v_mov_b32_e32 v4, v0
	v_mov_b32_e32 v5, v0
	v_mov_b32_e32 v6, v0
	v_mov_b32_e32 v7, v0
	v_mov_b32_e32 v8, v0
	v_mov_b32_e32 v9, v0
	v_mov_b32_e32 v10, v0
	v_mov_b32_e32 v11, v0
	v_mov_b32_e32 v12, v0
	v_mov_b32_e32 v13, v0
	v_mov_b32_e32 v14, v0
	v_mov_b32_e32 v15, v0
	v_mov_b32_e32 v16, v0
	v_mov_b32_e32 v17, v0
	v_mov_b32_e32 v18, v0
	v_mov_b32_e32 v19, v0
	v_mov_b32_e32 v20, v0
	v_mov_b32_e32 v21, v0
	v_mov_b32_e32 v22, v0
	v_mov_b32_e32 v23, v0
	v_mov_b32_e32 v24, v0
	v_mov_b32_e32 v25, v0
	v_mov_b32_e32 v26, v0
	v_mov_b32_e32 v27, v0
	v_mov_b32_e32 v28, v0
	v_mov_b32_e32 v29, v0
	v_mov_b32_e32 v30, v0
	v_mov_b32_e32 v31, v0
	s_barrier

.LBB0_412:
	s_or_b64 exec, exec, s[66:67]
	s_waitcnt lgkmcnt(0)
	v_add_f32_e32 v0, v1, v0
	s_lshl_b32 s0, s79, 2
	v_mul_f32_e32 v0, 0x3fb8aa3b, v0
	s_and_b32 s36, s0, 0xffffff00
	s_lshl_b64 s[0:1], s[4:5], 14
	v_exp_f32_e32 v0, v0
	s_add_u32 s24, s84, s0
	s_addc_u32 s25, s85, s1
	s_add_u32 s0, s82, s0
	v_lshl_or_b32 v1, v55, 2, s36
	s_addc_u32 s1, s83, s1
	v_lshlrev_b32_e32 v204, 1, v54
	ds_write_b32 v1, v0 offset:8192
	v_lshl_add_u64 v[0:1], s[0:1], 0, v[204:205]
	v_lshlrev_b32_e32 v2, 7, v206
	v_mov_b32_e32 v3, v205
	v_lshl_add_u64 v[16:17], v[0:1], 0, v[2:3]
	v_lshl_add_u64 v[20:21], s[24:25], 0, v[204:205]
	s_mov_b32 s98, s24
	s_mov_b32 s99, s25
	s_mov_b32 s100, s0
	s_mov_b32 s101, s1
	v_and_b32_e32 v226, 3, v206
	v_lshlrev_b32_e32 v226, 9, v226
	v_lshrrev_b32_e32 v227, 2, v206
	v_lshl_or_b32 v226, v227, 4, v226
	v_lshl_or_b32 v226, v56, 11, v226
	v_add_u32_e32 v227, 0x1000, v226
	v_add_u32_e32 v228, 0x2000, v226
	v_add_u32_e32 v229, 0x3000, v226
	s_waitcnt lgkmcnt(0)
	s_barrier
	global_load_dwordx4 v[4:7], v[16:17], off
	global_load_dwordx4 v[8:11], v[16:17], off offset:32
	v_lshl_add_u64 v[22:23], v[20:21], 0, v[2:3]
	global_load_dwordx4 v[120:123], v226, s[98:99]
	global_load_dwordx4 v[12:15], v[16:17], off offset:64
	v_mov_b32_e32 v25, v205
	v_or_b32_e32 v24, 0x1000, v2
	v_lshl_add_u64 v[26:27], v[20:21], 0, v[24:25]
	global_load_dwordx4 v[116:119], v226, s[98:99] offset:128
	global_load_dwordx4 v[112:115], v227, s[98:99]
	global_load_dwordx4 v[108:111], v227, s[98:99] offset:128
	global_load_dwordx4 v[104:107], v228, s[98:99]
	s_nop 0
	global_load_dwordx4 v[16:19], v[16:17], off offset:96
	v_mov_b32_e32 v29, v205
	v_or_b32_e32 v28, 0x2000, v2
	v_or_b32_e32 v2, 0x3000, v2
	global_load_dwordx4 v[100:103], v228, s[98:99] offset:128
	v_lshl_add_u64 v[30:31], v[20:21], 0, v[28:29]
	v_lshl_add_u64 v[20:21], v[20:21], 0, v[2:3]
	global_load_dwordx4 v[96:99], v229, s[98:99]
	global_load_dwordx4 v[92:95], v229, s[98:99] offset:128
	global_load_dwordx4 v[80:83], v226, s[98:99] offset:256
	global_load_dwordx4 v[76:79], v227, s[98:99] offset:256
	global_load_dwordx4 v[68:71], v228, s[98:99] offset:256
	global_load_dwordx4 v[64:67], v229, s[98:99] offset:256
	global_load_dwordx4 v[88:91], v226, s[98:99] offset:384
	global_load_dwordx4 v[84:87], v227, s[98:99] offset:384
	global_load_dwordx4 v[72:75], v228, s[98:99] offset:384
	v_and_or_b32 v126, v236, 32, s36
	ds_read_b128 v[148:151], v126 offset:8192
	ds_read_b128 v[144:147], v126 offset:8208
	ds_read_b128 v[128:131], v126 offset:8256
	ds_read_b128 v[132:135], v126 offset:8272
	ds_read_b128 v[136:139], v126 offset:8320
	ds_read_b128 v[140:143], v126 offset:8336
	ds_read_b128 v[156:159], v126 offset:8384
	ds_read_b128 v[152:155], v126 offset:8400
	v_lshl_add_u64 v[160:161], v[0:1], 0, v[2:3]
	s_mul_i32 s0, s4, 0x8100
	s_mul_hi_i32 s1, s4, 0x8100
	s_add_u32 s0, s88, s0
	s_addc_u32 s1, s89, s1
	v_lshl_add_u64 v[208:209], s[0:1], 0, v[204:205]
	v_lshlrev_b32_e32 v204, 8, v206
	v_lshl_add_u64 v[208:209], v[208:209], 0, v[204:205]
	s_movk_i32 s0, 0x6000
	v_cmp_eq_u32_e64 s[4:5], 0, v206
	s_waitcnt vmcnt(18)
	v_lshlrev_b32_e32 v22, 16, v4
	v_and_b32_e32 v23, 0xffff0000, v4
	v_lshlrev_b32_e32 v4, 16, v5
	v_and_b32_e32 v5, 0xffff0000, v5
	s_waitcnt vmcnt(17)
	v_lshlrev_b32_e32 v30, 16, v8
	v_and_b32_e32 v31, 0xffff0000, v8
	v_lshlrev_b32_e32 v8, 16, v9
	v_and_b32_e32 v9, 0xffff0000, v9
	s_waitcnt lgkmcnt(7)
	v_pk_mul_f32 v[22:23], v[148:149], v[22:23]
	v_pk_mul_f32 v[32:33], v[150:151], v[4:5]
	v_cvt_pk_bf16_f32 v4, v22, v23
	s_waitcnt vmcnt(15)
	v_lshlrev_b32_e32 v22, 16, v12
	v_and_b32_e32 v23, 0xffff0000, v12
	s_waitcnt lgkmcnt(5)
	v_pk_mul_f32 v[8:9], v[130:131], v[8:9]
	v_lshlrev_b32_e32 v124, 16, v10
	v_cvt_pk_bf16_f32 v211, v8, v9
	s_waitcnt lgkmcnt(3)
	v_pk_mul_f32 v[8:9], v[136:137], v[22:23]
	v_and_b32_e32 v125, 0xffff0000, v10
	v_cvt_pk_bf16_f32 v214, v8, v9
	s_waitcnt vmcnt(10)
	v_lshlrev_b32_e32 v8, 16, v16
	v_and_b32_e32 v9, 0xffff0000, v16
	s_waitcnt lgkmcnt(1)
	v_pk_mul_f32 v[8:9], v[156:157], v[8:9]
	v_pk_mul_f32 v[124:125], v[132:133], v[124:125]
	v_cvt_pk_bf16_f32 v218, v8, v9
	v_lshl_add_u64 v[8:9], v[0:1], 0, v[24:25]
	v_cvt_pk_bf16_f32 v212, v124, v125
	global_load_dwordx4 v[124:127], v229, s[98:99] offset:384
	global_load_dwordx4 v[222:225], v[8:9], off
	global_load_dwordx4 v[200:203], v[8:9], off offset:32
	global_load_dwordx4 v[196:199], v[8:9], off offset:64
	global_load_dwordx4 v[192:195], v[8:9], off offset:96
	v_lshlrev_b32_e32 v26, 16, v6
	v_and_b32_e32 v27, 0xffff0000, v6
	v_lshlrev_b32_e32 v6, 16, v7
	v_and_b32_e32 v7, 0xffff0000, v7
	v_lshlrev_b32_e32 v10, 16, v11
	v_and_b32_e32 v11, 0xffff0000, v11
	v_pk_mul_f32 v[26:27], v[144:145], v[26:27]
	v_pk_mul_f32 v[34:35], v[146:147], v[6:7]
	v_cvt_pk_bf16_f32 v6, v26, v27
	v_lshlrev_b32_e32 v12, 16, v13
	v_and_b32_e32 v13, 0xffff0000, v13
	v_lshlrev_b32_e32 v26, 16, v14
	v_and_b32_e32 v27, 0xffff0000, v14
	v_pk_mul_f32 v[10:11], v[134:135], v[10:11]
	v_lshlrev_b32_e32 v14, 16, v15
	v_and_b32_e32 v15, 0xffff0000, v15
	v_lshl_add_u64 v[8:9], v[0:1], 0, v[28:29]
	v_cvt_pk_bf16_f32 v5, v32, v33
	v_cvt_pk_bf16_f32 v7, v34, v35
	v_pk_mul_f32 v[30:31], v[128:129], v[30:31]
	v_cvt_pk_bf16_f32 v213, v10, v11
	v_pk_mul_f32 v[10:11], v[138:139], v[12:13]
	v_pk_mul_f32 v[12:13], v[140:141], v[26:27]
	v_pk_mul_f32 v[14:15], v[142:143], v[14:15]
	global_load_dwordx4 v[188:191], v[8:9], off
	global_load_dwordx4 v[184:187], v[8:9], off offset:32
	global_load_dwordx4 v[180:183], v[8:9], off offset:64
	global_load_dwordx4 v[176:179], v[8:9], off offset:96
	v_cvt_pk_bf16_f32 v210, v30, v31
	v_cvt_pk_bf16_f32 v215, v10, v11
	v_cvt_pk_bf16_f32 v216, v12, v13
	v_cvt_pk_bf16_f32 v217, v14, v15
	v_lshlrev_b32_e32 v10, 16, v17
	v_and_b32_e32 v11, 0xffff0000, v17
	v_lshlrev_b32_e32 v12, 16, v18
	v_and_b32_e32 v13, 0xffff0000, v18
	v_lshlrev_b32_e32 v14, 16, v19
	v_and_b32_e32 v15, 0xffff0000, v19
	s_waitcnt vmcnt(15)
	v_mfma_f32_32x32x16_bf16 v[16:31], v[80:83], v[4:7], 0
	v_mul_f32_e64 v10, v158, v10
	v_mul_f32_e64 v11, v159, v11
	s_waitcnt lgkmcnt(0)
	v_mul_f32_e64 v12, v152, v12
	v_mul_f32_e64 v13, v153, v13
	v_pk_mul_f32 v[14:15], v[154:155], v[14:15]
	v_cvt_pk_bf16_f32 v219, v10, v11
	v_cvt_pk_bf16_f32 v220, v12, v13
	v_cvt_pk_bf16_f32 v221, v14, v15
	global_load_dwordx4 v[172:175], v[160:161], off
	global_load_dwordx4 v[168:171], v[160:161], off offset:32
	s_waitcnt vmcnt(16)
	v_mfma_f32_32x32x16_bf16 v[16:31], v[76:79], v[210:213], v[16:31]
	global_load_dwordx4 v[164:167], v[160:161], off offset:64
	s_nop 0
	global_load_dwordx4 v[160:163], v[160:161], off offset:96
	v_mfma_f32_32x32x16_bf16 v[32:47], v[116:119], v[4:7], 0
	s_waitcnt vmcnt(17)
	v_mfma_f32_32x32x16_bf16 v[16:31], v[68:71], v[214:217], v[16:31]
	v_mfma_f32_32x32x16_bf16 v[48:63], v[120:123], v[4:7], 0
	v_mfma_f32_32x32x16_bf16 v[32:47], v[108:111], v[210:213], v[32:47]
	s_waitcnt vmcnt(15)
	v_mfma_f32_32x32x16_bf16 v[0:15], v[88:91], v[4:7], 0
	v_mfma_f32_32x32x16_bf16 v[16:31], v[64:67], v[218:221], v[16:31]
	v_mfma_f32_32x32x16_bf16 v[48:63], v[112:115], v[210:213], v[48:63]
	s_nop 10
	v_cvt_pk_bf16_f32 v16, v16, v17
	v_cvt_pk_bf16_f32 v17, v18, v19
	v_cvt_pk_bf16_f32 v18, v20, v21
	v_cvt_pk_bf16_f32 v19, v22, v23
	s_nop 0
	v_permlane32_swap_b32_e32 v16, v18
	v_permlane32_swap_b32_e32 v17, v19
	v_mfma_f32_32x32x16_bf16 v[32:47], v[100:103], v[214:217], v[32:47]
	global_store_dwordx4 v[208:209], v[16:19], off offset:128
	s_waitcnt vmcnt(12)
	v_lshlrev_b32_e32 v20, 16, v222
	v_and_b32_e32 v21, 0xffff0000, v222
	v_cvt_pk_bf16_f32 v16, v24, v25
	v_cvt_pk_bf16_f32 v17, v26, v27
	v_lshlrev_b32_e32 v22, 16, v223
	v_and_b32_e32 v23, 0xffff0000, v223
	v_mfma_f32_32x32x16_bf16 v[0:15], v[84:87], v[210:213], v[0:15]
	v_lshlrev_b32_e32 v24, 16, v224
	v_and_b32_e32 v25, 0xffff0000, v224
	v_lshlrev_b32_e32 v26, 16, v225
	v_and_b32_e32 v27, 0xffff0000, v225
	v_mul_f32_e64 v20, v148, v20
	v_mul_f32_e64 v21, v149, v21
	v_pk_mul_f32 v[22:23], v[150:151], v[22:23]
	v_pk_mul_f32 v[24:25], v[144:145], v[24:25]
	v_mfma_f32_32x32x16_bf16 v[48:63], v[104:107], v[214:217], v[48:63]
	v_mul_f32_e64 v26, v146, v26
	v_mul_f32_e64 v27, v147, v27
	v_cvt_pk_bf16_f32 v210, v20, v21
	v_cvt_pk_bf16_f32 v211, v22, v23
	v_cvt_pk_bf16_f32 v212, v24, v25
	v_cvt_pk_bf16_f32 v213, v26, v27
	s_waitcnt vmcnt(11)
	v_lshlrev_b32_e32 v20, 16, v200
	v_and_b32_e32 v21, 0xffff0000, v200
	v_lshlrev_b32_e32 v22, 16, v201
	v_and_b32_e32 v23, 0xffff0000, v201
	v_lshlrev_b32_e32 v24, 16, v202
	v_and_b32_e32 v25, 0xffff0000, v202
	v_lshlrev_b32_e32 v26, 16, v203
	v_and_b32_e32 v27, 0xffff0000, v203
	v_pk_mul_f32 v[20:21], v[128:129], v[20:21]
	v_pk_mul_f32 v[22:23], v[130:131], v[22:23]
	v_pk_mul_f32 v[24:25], v[132:133], v[24:25]
	v_pk_mul_f32 v[26:27], v[134:135], v[26:27]
	v_cvt_pk_bf16_f32 v200, v20, v21
	v_cvt_pk_bf16_f32 v201, v22, v23
	v_cvt_pk_bf16_f32 v202, v24, v25
	v_cvt_pk_bf16_f32 v203, v26, v27
	s_waitcnt vmcnt(10)
	v_lshlrev_b32_e32 v20, 16, v196
	v_and_b32_e32 v21, 0xffff0000, v196
	v_lshlrev_b32_e32 v22, 16, v197
	v_and_b32_e32 v23, 0xffff0000, v197
	v_lshlrev_b32_e32 v24, 16, v198
	v_and_b32_e32 v25, 0xffff0000, v198
	v_lshlrev_b32_e32 v26, 16, v199
	v_and_b32_e32 v27, 0xffff0000, v199
	v_pk_mul_f32 v[20:21], v[136:137], v[20:21]
	v_pk_mul_f32 v[22:23], v[138:139], v[22:23]
	v_pk_mul_f32 v[24:25], v[140:141], v[24:25]
	v_pk_mul_f32 v[26:27], v[142:143], v[26:27]
	v_mfma_f32_32x32x16_bf16 v[32:47], v[92:95], v[218:221], v[32:47]
	v_cvt_pk_bf16_f32 v18, v28, v29
	v_cvt_pk_bf16_f32 v196, v20, v21
	v_cvt_pk_bf16_f32 v197, v22, v23
	v_cvt_pk_bf16_f32 v198, v24, v25
	v_cvt_pk_bf16_f32 v199, v26, v27
	s_waitcnt vmcnt(9)
	v_lshlrev_b32_e32 v20, 16, v192
	v_and_b32_e32 v21, 0xffff0000, v192
	v_mfma_f32_32x32x16_bf16 v[0:15], v[72:75], v[214:217], v[0:15]
	v_lshlrev_b32_e32 v22, 16, v193
	v_and_b32_e32 v23, 0xffff0000, v193
	v_lshlrev_b32_e32 v24, 16, v194
	v_and_b32_e32 v25, 0xffff0000, v194
	v_lshlrev_b32_e32 v26, 16, v195
	v_and_b32_e32 v27, 0xffff0000, v195
	v_cvt_pk_bf16_f32 v19, v30, v31
	v_pk_mul_f32 v[20:21], v[156:157], v[20:21]
	v_pk_mul_f32 v[22:23], v[158:159], v[22:23]
	v_pk_mul_f32 v[24:25], v[152:153], v[24:25]
	v_pk_mul_f32 v[26:27], v[154:155], v[26:27]
	v_permlane32_swap_b32_e32 v16, v18
	v_permlane32_swap_b32_e32 v17, v19
	v_mfma_f32_32x32x16_bf16 v[48:63], v[96:99], v[218:221], v[48:63]
	v_cvt_pk_bf16_f32 v214, v20, v21
	v_cvt_pk_bf16_f32 v215, v22, v23
	v_cvt_pk_bf16_f32 v216, v24, v25
	v_cvt_pk_bf16_f32 v217, v26, v27
	global_store_dwordx4 v[208:209], v[16:19], off offset:160
	v_cvt_pk_bf16_f32 v32, v32, v33
	v_cvt_pk_bf16_f32 v33, v34, v35
	v_mfma_f32_32x32x16_bf16 v[16:31], v[80:83], v[210:213], 0
	v_cvt_pk_bf16_f32 v34, v36, v37
	v_cvt_pk_bf16_f32 v35, v38, v39
	s_nop 0
	v_permlane32_swap_b32_e32 v32, v34
	v_permlane32_swap_b32_e32 v33, v35
	v_cvt_pk_bf16_f32 v48, v48, v49
	v_mfma_f32_32x32x16_bf16 v[0:15], v[124:127], v[218:221], v[0:15]
	v_cvt_pk_bf16_f32 v49, v50, v51
	v_cvt_pk_bf16_f32 v50, v52, v53
	v_cvt_pk_bf16_f32 v51, v54, v55
	global_store_dwordx4 v[208:209], v[32:35], off offset:64
	v_permlane32_swap_b32_e32 v48, v50
	s_nop 0
	v_cvt_pk_bf16_f32 v32, v40, v41
	v_cvt_pk_bf16_f32 v33, v42, v43
	v_cvt_pk_bf16_f32 v34, v44, v45
	v_cvt_pk_bf16_f32 v35, v46, v47
	v_mfma_f32_32x32x16_bf16 v[16:31], v[76:79], v[200:203], v[16:31]
	v_permlane32_swap_b32_e32 v49, v51
	v_permlane32_swap_b32_e32 v32, v34
	v_permlane32_swap_b32_e32 v33, v35
	global_store_dwordx4 v[208:209], v[48:51], off
	global_store_dwordx4 v[208:209], v[32:35], off offset:96
	v_cvt_pk_bf16_f32 v0, v0, v1
	v_cvt_pk_bf16_f32 v48, v56, v57
	v_cvt_pk_bf16_f32 v49, v58, v59
	v_cvt_pk_bf16_f32 v50, v60, v61
	v_cvt_pk_bf16_f32 v51, v62, v63
	v_mfma_f32_32x32x16_bf16 v[32:47], v[116:119], v[210:213], 0
	v_permlane32_swap_b32_e32 v48, v50
	v_permlane32_swap_b32_e32 v49, v51
	global_store_dwordx4 v[208:209], v[48:51], off offset:32
	v_cvt_pk_bf16_f32 v1, v2, v3
	v_cvt_pk_bf16_f32 v2, v4, v5
	v_mfma_f32_32x32x16_bf16 v[48:63], v[120:123], v[210:213], 0
	v_cvt_pk_bf16_f32 v3, v6, v7
	v_permlane32_swap_b32_e32 v0, v2
	s_nop 0
	v_permlane32_swap_b32_e32 v1, v3
	global_store_dwordx4 v[208:209], v[0:3], off offset:192
	v_cvt_pk_bf16_f32 v192, v8, v9
	v_cvt_pk_bf16_f32 v193, v10, v11
	v_cvt_pk_bf16_f32 v194, v12, v13
	v_cvt_pk_bf16_f32 v195, v14, v15
	v_mfma_f32_32x32x16_bf16 v[0:15], v[88:91], v[210:213], 0
	v_permlane32_swap_b32_e32 v192, v194
	v_permlane32_swap_b32_e32 v193, v195
	global_store_dwordx4 v[208:209], v[192:195], off offset:224
	v_mfma_f32_32x32x16_bf16 v[16:31], v[68:71], v[196:199], v[16:31]
	s_nop 0
	v_add_co_u32_e32 v192, vcc, s94, v208
	s_nop 1
	v_addc_co_u32_e32 v193, vcc, 0, v209, vcc
	v_mfma_f32_32x32x16_bf16 v[32:47], v[108:111], v[200:203], v[32:47]
	v_mfma_f32_32x32x16_bf16 v[48:63], v[112:115], v[200:203], v[48:63]
	v_mfma_f32_32x32x16_bf16 v[0:15], v[84:87], v[200:203], v[0:15]
	v_mfma_f32_32x32x16_bf16 v[16:31], v[64:67], v[214:217], v[16:31]
	v_mfma_f32_32x32x16_bf16 v[32:47], v[100:103], v[196:199], v[32:47]
	s_nop 10
	v_cvt_pk_bf16_f32 v16, v16, v17
	v_cvt_pk_bf16_f32 v17, v18, v19
	v_cvt_pk_bf16_f32 v18, v20, v21
	v_cvt_pk_bf16_f32 v19, v22, v23
	s_nop 0
	v_permlane32_swap_b32_e32 v16, v18
	v_permlane32_swap_b32_e32 v17, v19
	v_mfma_f32_32x32x16_bf16 v[48:63], v[104:107], v[196:199], v[48:63]
	global_store_dwordx4 v[192:193], v[16:19], off offset:128
	s_waitcnt vmcnt(16)
	v_lshlrev_b32_e32 v20, 16, v188
	v_and_b32_e32 v21, 0xffff0000, v188
	v_cvt_pk_bf16_f32 v16, v24, v25
	v_cvt_pk_bf16_f32 v17, v26, v27
	v_lshlrev_b32_e32 v22, 16, v189
	v_and_b32_e32 v23, 0xffff0000, v189
	v_mfma_f32_32x32x16_bf16 v[0:15], v[72:75], v[196:199], v[0:15]
	v_lshlrev_b32_e32 v24, 16, v190
	v_and_b32_e32 v25, 0xffff0000, v190
	v_lshlrev_b32_e32 v26, 16, v191
	v_and_b32_e32 v27, 0xffff0000, v191
	v_mul_f32_e64 v20, v148, v20
	v_mul_f32_e64 v21, v149, v21
	v_pk_mul_f32 v[22:23], v[150:151], v[22:23]
	v_pk_mul_f32 v[24:25], v[144:145], v[24:25]
	v_mfma_f32_32x32x16_bf16 v[32:47], v[92:95], v[214:217], v[32:47]
	v_mul_f32_e64 v26, v146, v26
	v_mul_f32_e64 v27, v147, v27
	v_cvt_pk_bf16_f32 v188, v20, v21
	v_cvt_pk_bf16_f32 v189, v22, v23
	v_cvt_pk_bf16_f32 v190, v24, v25
	v_cvt_pk_bf16_f32 v191, v26, v27
	s_waitcnt vmcnt(15)
	v_lshlrev_b32_e32 v20, 16, v184
	v_and_b32_e32 v21, 0xffff0000, v184
	v_mfma_f32_32x32x16_bf16 v[48:63], v[96:99], v[214:217], v[48:63]
	v_lshlrev_b32_e32 v22, 16, v185
	v_and_b32_e32 v23, 0xffff0000, v185
	v_lshlrev_b32_e32 v24, 16, v186
	v_and_b32_e32 v25, 0xffff0000, v186
	v_lshlrev_b32_e32 v26, 16, v187
	v_and_b32_e32 v27, 0xffff0000, v187
	v_pk_mul_f32 v[20:21], v[128:129], v[20:21]
	v_pk_mul_f32 v[22:23], v[130:131], v[22:23]
	v_pk_mul_f32 v[24:25], v[132:133], v[24:25]
	v_pk_mul_f32 v[26:27], v[134:135], v[26:27]
	v_cvt_pk_bf16_f32 v184, v20, v21
	v_cvt_pk_bf16_f32 v185, v22, v23
	v_cvt_pk_bf16_f32 v186, v24, v25
	v_cvt_pk_bf16_f32 v187, v26, v27
	s_waitcnt vmcnt(14)
	v_lshlrev_b32_e32 v20, 16, v180
	v_and_b32_e32 v21, 0xffff0000, v180
	v_lshlrev_b32_e32 v22, 16, v181
	v_and_b32_e32 v23, 0xffff0000, v181
	v_lshlrev_b32_e32 v24, 16, v182
	v_and_b32_e32 v25, 0xffff0000, v182
	v_lshlrev_b32_e32 v26, 16, v183
	v_and_b32_e32 v27, 0xffff0000, v183
	v_pk_mul_f32 v[20:21], v[136:137], v[20:21]
	v_pk_mul_f32 v[22:23], v[138:139], v[22:23]
	v_pk_mul_f32 v[24:25], v[140:141], v[24:25]
	v_pk_mul_f32 v[26:27], v[142:143], v[26:27]
	v_mfma_f32_32x32x16_bf16 v[0:15], v[124:127], v[214:217], v[0:15]
	v_cvt_pk_bf16_f32 v18, v28, v29
	v_cvt_pk_bf16_f32 v180, v20, v21
	v_cvt_pk_bf16_f32 v181, v22, v23
	v_cvt_pk_bf16_f32 v182, v24, v25
	v_cvt_pk_bf16_f32 v183, v26, v27
	s_waitcnt vmcnt(13)
	v_lshlrev_b32_e32 v20, 16, v176
	v_and_b32_e32 v21, 0xffff0000, v176
	v_lshlrev_b32_e32 v22, 16, v177
	v_and_b32_e32 v23, 0xffff0000, v177
	v_lshlrev_b32_e32 v24, 16, v178
	v_and_b32_e32 v25, 0xffff0000, v178
	v_lshlrev_b32_e32 v26, 16, v179
	v_and_b32_e32 v27, 0xffff0000, v179
	v_cvt_pk_bf16_f32 v19, v30, v31
	v_pk_mul_f32 v[20:21], v[156:157], v[20:21]
	v_pk_mul_f32 v[22:23], v[158:159], v[22:23]
	v_pk_mul_f32 v[24:25], v[152:153], v[24:25]
	v_pk_mul_f32 v[26:27], v[154:155], v[26:27]
	v_permlane32_swap_b32_e32 v16, v18
	v_permlane32_swap_b32_e32 v17, v19
	v_cvt_pk_bf16_f32 v32, v32, v33
	v_cvt_pk_bf16_f32 v33, v34, v35
	v_cvt_pk_bf16_f32 v34, v36, v37
	v_cvt_pk_bf16_f32 v35, v38, v39
	v_cvt_pk_bf16_f32 v194, v20, v21
	v_cvt_pk_bf16_f32 v195, v22, v23
	v_cvt_pk_bf16_f32 v196, v24, v25
	v_cvt_pk_bf16_f32 v197, v26, v27
	global_store_dwordx4 v[192:193], v[16:19], off offset:160
	v_permlane32_swap_b32_e32 v32, v34
	s_nop 0
	v_mfma_f32_32x32x16_bf16 v[16:31], v[80:83], v[188:191], 0
	v_permlane32_swap_b32_e32 v33, v35
	v_cvt_pk_bf16_f32 v48, v48, v49
	v_cvt_pk_bf16_f32 v49, v50, v51
	v_cvt_pk_bf16_f32 v50, v52, v53
	v_cvt_pk_bf16_f32 v51, v54, v55
	global_store_dwordx4 v[192:193], v[32:35], off offset:64
	v_permlane32_swap_b32_e32 v48, v50
	s_nop 0
	v_cvt_pk_bf16_f32 v32, v40, v41
	v_cvt_pk_bf16_f32 v33, v42, v43
	v_cvt_pk_bf16_f32 v34, v44, v45
	v_cvt_pk_bf16_f32 v35, v46, v47
	v_permlane32_swap_b32_e32 v49, v51
	v_permlane32_swap_b32_e32 v32, v34
	v_permlane32_swap_b32_e32 v33, v35
	global_store_dwordx4 v[192:193], v[48:51], off
	global_store_dwordx4 v[192:193], v[32:35], off offset:96
	v_cvt_pk_bf16_f32 v0, v0, v1
	v_cvt_pk_bf16_f32 v48, v56, v57
	v_cvt_pk_bf16_f32 v49, v58, v59
	v_cvt_pk_bf16_f32 v50, v60, v61
	v_cvt_pk_bf16_f32 v51, v62, v63
	v_mfma_f32_32x32x16_bf16 v[32:47], v[116:119], v[188:191], 0
	v_permlane32_swap_b32_e32 v48, v50
	v_permlane32_swap_b32_e32 v49, v51
	global_store_dwordx4 v[192:193], v[48:51], off offset:32
	v_cvt_pk_bf16_f32 v1, v2, v3
	v_cvt_pk_bf16_f32 v2, v4, v5
	v_mfma_f32_32x32x16_bf16 v[48:63], v[120:123], v[188:191], 0
	v_cvt_pk_bf16_f32 v3, v6, v7
	v_permlane32_swap_b32_e32 v0, v2
	s_nop 0
	v_permlane32_swap_b32_e32 v1, v3
	global_store_dwordx4 v[192:193], v[0:3], off offset:192
	v_cvt_pk_bf16_f32 v176, v8, v9
	v_cvt_pk_bf16_f32 v177, v10, v11
	v_cvt_pk_bf16_f32 v178, v12, v13
	v_cvt_pk_bf16_f32 v179, v14, v15
	v_mfma_f32_32x32x16_bf16 v[0:15], v[88:91], v[188:191], 0
	v_permlane32_swap_b32_e32 v176, v178
	v_permlane32_swap_b32_e32 v177, v179
	global_store_dwordx4 v[192:193], v[176:179], off offset:224
	v_mfma_f32_32x32x16_bf16 v[16:31], v[76:79], v[184:187], v[16:31]
	s_nop 0
	v_add_co_u32_e32 v176, vcc, s95, v208
	s_nop 1
	v_addc_co_u32_e32 v177, vcc, 0, v209, vcc
	v_mfma_f32_32x32x16_bf16 v[32:47], v[108:111], v[184:187], v[32:47]
	v_mfma_f32_32x32x16_bf16 v[48:63], v[112:115], v[184:187], v[48:63]
	v_mfma_f32_32x32x16_bf16 v[0:15], v[84:87], v[184:187], v[0:15]
	v_mfma_f32_32x32x16_bf16 v[16:31], v[68:71], v[180:183], v[16:31]
	v_mfma_f32_32x32x16_bf16 v[32:47], v[100:103], v[180:183], v[32:47]
	v_mfma_f32_32x32x16_bf16 v[48:63], v[104:107], v[180:183], v[48:63]
	v_mfma_f32_32x32x16_bf16 v[0:15], v[72:75], v[180:183], v[0:15]
	v_mfma_f32_32x32x16_bf16 v[16:31], v[64:67], v[194:197], v[16:31]
	v_mfma_f32_32x32x16_bf16 v[32:47], v[92:95], v[194:197], v[32:47]
	s_nop 10
	v_cvt_pk_bf16_f32 v16, v16, v17
	v_cvt_pk_bf16_f32 v17, v18, v19
	v_cvt_pk_bf16_f32 v18, v20, v21
	v_cvt_pk_bf16_f32 v19, v22, v23
	s_nop 0
	v_permlane32_swap_b32_e32 v16, v18
	v_permlane32_swap_b32_e32 v17, v19
	v_mfma_f32_32x32x16_bf16 v[48:63], v[96:99], v[194:197], v[48:63]
	global_store_dwordx4 v[176:177], v[16:19], off offset:128
	s_waitcnt vmcnt(20)
	v_lshlrev_b32_e32 v20, 16, v172
	v_and_b32_e32 v21, 0xffff0000, v172
	v_cvt_pk_bf16_f32 v16, v24, v25
	v_cvt_pk_bf16_f32 v17, v26, v27
	v_lshlrev_b32_e32 v22, 16, v173
	v_and_b32_e32 v23, 0xffff0000, v173
	v_mfma_f32_32x32x16_bf16 v[0:15], v[124:127], v[194:197], v[0:15]
	v_lshlrev_b32_e32 v24, 16, v174
	v_and_b32_e32 v25, 0xffff0000, v174
	v_lshlrev_b32_e32 v26, 16, v175
	v_and_b32_e32 v27, 0xffff0000, v175
	v_mul_f32_e64 v20, v148, v20
	v_mul_f32_e64 v21, v149, v21
	v_pk_mul_f32 v[22:23], v[150:151], v[22:23]
	v_pk_mul_f32 v[24:25], v[144:145], v[24:25]
	v_pk_mul_f32 v[26:27], v[146:147], v[26:27]
	v_cvt_pk_bf16_f32 v32, v32, v33
	v_cvt_pk_bf16_f32 v33, v34, v35
	v_cvt_pk_bf16_f32 v34, v36, v37
	v_cvt_pk_bf16_f32 v35, v38, v39
	v_cvt_pk_bf16_f32 v172, v20, v21
	v_cvt_pk_bf16_f32 v173, v22, v23
	v_cvt_pk_bf16_f32 v174, v24, v25
	v_cvt_pk_bf16_f32 v175, v26, v27
	s_waitcnt vmcnt(19)
	v_lshlrev_b32_e32 v20, 16, v168
	v_and_b32_e32 v21, 0xffff0000, v168
	v_lshlrev_b32_e32 v22, 16, v169
	v_and_b32_e32 v23, 0xffff0000, v169
	v_lshlrev_b32_e32 v24, 16, v170
	v_and_b32_e32 v25, 0xffff0000, v170
	v_lshlrev_b32_e32 v26, 16, v171
	v_and_b32_e32 v27, 0xffff0000, v171
	v_permlane32_swap_b32_e32 v32, v34
	v_permlane32_swap_b32_e32 v33, v35
	v_pk_mul_f32 v[20:21], v[128:129], v[20:21]
	v_pk_mul_f32 v[22:23], v[130:131], v[22:23]
	v_pk_mul_f32 v[24:25], v[132:133], v[24:25]
	v_pk_mul_f32 v[26:27], v[134:135], v[26:27]
	v_cvt_pk_bf16_f32 v48, v48, v49
	v_cvt_pk_bf16_f32 v49, v50, v51
	v_cvt_pk_bf16_f32 v50, v52, v53
	v_cvt_pk_bf16_f32 v51, v54, v55
	global_store_dwordx4 v[176:177], v[32:35], off offset:64
	v_cvt_pk_bf16_f32 v168, v20, v21
	v_cvt_pk_bf16_f32 v169, v22, v23
	v_cvt_pk_bf16_f32 v32, v40, v41
	v_cvt_pk_bf16_f32 v33, v42, v43
	v_cvt_pk_bf16_f32 v34, v44, v45
	v_cvt_pk_bf16_f32 v35, v46, v47
	v_cvt_pk_bf16_f32 v170, v24, v25
	v_cvt_pk_bf16_f32 v171, v26, v27
	s_waitcnt vmcnt(19)
	v_lshlrev_b32_e32 v20, 16, v164
	v_and_b32_e32 v21, 0xffff0000, v164
	v_lshlrev_b32_e32 v22, 16, v165
	v_and_b32_e32 v23, 0xffff0000, v165
	v_lshlrev_b32_e32 v24, 16, v166
	v_and_b32_e32 v25, 0xffff0000, v166
	v_lshlrev_b32_e32 v26, 16, v167
	v_and_b32_e32 v27, 0xffff0000, v167
	v_permlane32_swap_b32_e32 v48, v50
	v_permlane32_swap_b32_e32 v49, v51
	v_permlane32_swap_b32_e32 v32, v34
	v_permlane32_swap_b32_e32 v33, v35
	v_pk_mul_f32 v[20:21], v[136:137], v[20:21]
	v_pk_mul_f32 v[22:23], v[138:139], v[22:23]
	v_pk_mul_f32 v[24:25], v[140:141], v[24:25]
	v_pk_mul_f32 v[26:27], v[142:143], v[26:27]
	global_store_dwordx4 v[176:177], v[48:51], off
	global_store_dwordx4 v[176:177], v[32:35], off offset:96
	v_cvt_pk_bf16_f32 v18, v28, v29
	v_cvt_pk_bf16_f32 v48, v56, v57
	v_cvt_pk_bf16_f32 v49, v58, v59
	v_cvt_pk_bf16_f32 v50, v60, v61
	v_cvt_pk_bf16_f32 v51, v62, v63
	v_mfma_f32_32x32x16_bf16 v[32:47], v[116:119], v[172:175], 0
	v_cvt_pk_bf16_f32 v164, v20, v21
	v_cvt_pk_bf16_f32 v165, v22, v23
	v_cvt_pk_bf16_f32 v166, v24, v25
	v_cvt_pk_bf16_f32 v167, v26, v27
	s_waitcnt vmcnt(20)
	v_lshlrev_b32_e32 v20, 16, v160
	v_and_b32_e32 v21, 0xffff0000, v160
	v_lshlrev_b32_e32 v22, 16, v161
	v_and_b32_e32 v23, 0xffff0000, v161
	v_lshlrev_b32_e32 v24, 16, v162
	v_and_b32_e32 v25, 0xffff0000, v162
	v_lshlrev_b32_e32 v26, 16, v163
	v_and_b32_e32 v27, 0xffff0000, v163
	v_cvt_pk_bf16_f32 v19, v30, v31
	v_cvt_pk_bf16_f32 v0, v0, v1
	v_cvt_pk_bf16_f32 v1, v2, v3
	v_cvt_pk_bf16_f32 v2, v4, v5
	v_cvt_pk_bf16_f32 v3, v6, v7
	v_permlane32_swap_b32_e32 v48, v50
	v_permlane32_swap_b32_e32 v49, v51
	v_pk_mul_f32 v[20:21], v[156:157], v[20:21]
	v_pk_mul_f32 v[22:23], v[158:159], v[22:23]
	v_pk_mul_f32 v[24:25], v[152:153], v[24:25]
	v_pk_mul_f32 v[26:27], v[154:155], v[26:27]
	v_permlane32_swap_b32_e32 v16, v18
	v_permlane32_swap_b32_e32 v17, v19
	v_permlane32_swap_b32_e32 v0, v2
	v_permlane32_swap_b32_e32 v1, v3
	global_store_dwordx4 v[176:177], v[48:51], off offset:32
	v_cvt_pk_bf16_f32 v160, v20, v21
	v_cvt_pk_bf16_f32 v161, v22, v23
	v_mfma_f32_32x32x16_bf16 v[48:63], v[120:123], v[172:175], 0
	v_cvt_pk_bf16_f32 v162, v24, v25
	v_cvt_pk_bf16_f32 v163, v26, v27
	global_store_dwordx4 v[176:177], v[16:19], off offset:160
	global_store_dwordx4 v[176:177], v[0:3], off offset:192
	v_cvt_pk_bf16_f32 v178, v8, v9
	v_cvt_pk_bf16_f32 v179, v10, v11
	v_cvt_pk_bf16_f32 v180, v12, v13
	v_mfma_f32_32x32x16_bf16 v[16:31], v[80:83], v[172:175], 0
	v_cvt_pk_bf16_f32 v181, v14, v15
	v_permlane32_swap_b32_e32 v178, v180
	s_nop 0
	v_permlane32_swap_b32_e32 v179, v181
	global_store_dwordx4 v[176:177], v[178:181], off offset:224
	v_mfma_f32_32x32x16_bf16 v[0:15], v[88:91], v[172:175], 0
	v_add_co_u32_e32 v172, vcc, s0, v208
	s_nop 1
	v_addc_co_u32_e32 v173, vcc, 0, v209, vcc
	v_mfma_f32_32x32x16_bf16 v[32:47], v[108:111], v[168:171], v[32:47]
	v_mfma_f32_32x32x16_bf16 v[48:63], v[112:115], v[168:171], v[48:63]
	v_mfma_f32_32x32x16_bf16 v[16:31], v[76:79], v[168:171], v[16:31]
	v_mfma_f32_32x32x16_bf16 v[0:15], v[84:87], v[168:171], v[0:15]
	v_mfma_f32_32x32x16_bf16 v[32:47], v[100:103], v[164:167], v[32:47]
	v_mfma_f32_32x32x16_bf16 v[48:63], v[104:107], v[164:167], v[48:63]
	v_mfma_f32_32x32x16_bf16 v[16:31], v[68:71], v[164:167], v[16:31]
	v_mfma_f32_32x32x16_bf16 v[0:15], v[72:75], v[164:167], v[0:15]
	v_mfma_f32_32x32x16_bf16 v[32:47], v[92:95], v[160:163], v[32:47]
	v_mfma_f32_32x32x16_bf16 v[48:63], v[96:99], v[160:163], v[48:63]
	s_nop 10
	v_cvt_pk_bf16_f32 v32, v32, v33
	v_cvt_pk_bf16_f32 v33, v34, v35
	v_cvt_pk_bf16_f32 v34, v36, v37
	v_cvt_pk_bf16_f32 v35, v38, v39
	s_nop 0
	v_permlane32_swap_b32_e32 v32, v34
	v_permlane32_swap_b32_e32 v33, v35
	v_mfma_f32_32x32x16_bf16 v[16:31], v[64:67], v[160:163], v[16:31]
	v_cvt_pk_bf16_f32 v48, v48, v49
	v_cvt_pk_bf16_f32 v49, v50, v51
	v_cvt_pk_bf16_f32 v50, v52, v53
	v_cvt_pk_bf16_f32 v51, v54, v55
	global_store_dwordx4 v[172:173], v[32:35], off offset:64
	v_permlane32_swap_b32_e32 v48, v50
	v_mfma_f32_32x32x16_bf16 v[0:15], v[124:127], v[160:163], v[0:15]
	v_cvt_pk_bf16_f32 v32, v40, v41
	v_cvt_pk_bf16_f32 v33, v42, v43
	v_cvt_pk_bf16_f32 v34, v44, v45
	v_cvt_pk_bf16_f32 v35, v46, v47
	s_nop 0
	v_cvt_pk_bf16_f32 v16, v16, v17
	v_cvt_pk_bf16_f32 v17, v18, v19
	v_cvt_pk_bf16_f32 v18, v20, v21
	v_cvt_pk_bf16_f32 v19, v22, v23
	s_nop 2
	v_cvt_pk_bf16_f32 v52, v0, v1
	v_cvt_pk_bf16_f32 v53, v2, v3
	v_cvt_pk_bf16_f32 v54, v4, v5
	v_cvt_pk_bf16_f32 v55, v6, v7
	v_cndmask_b32_e64 v0, 0, v148, s[4:5]
	v_cndmask_b32_e64 v1, 0, v149, s[4:5]
	v_cndmask_b32_e64 v2, 0, v150, s[4:5]
	v_cndmask_b32_e64 v3, 0, v151, s[4:5]
	v_cndmask_b32_e64 v4, 0, v144, s[4:5]
	v_cndmask_b32_e64 v5, 0, v145, s[4:5]
	v_cndmask_b32_e64 v6, 0, v146, s[4:5]
	v_cndmask_b32_e64 v7, 0, v147, s[4:5]
	v_permlane32_swap_b32_e32 v32, v34
	v_permlane32_swap_b32_e32 v33, v35
	v_permlane32_swap_b32_e32 v16, v18
	v_permlane32_swap_b32_e32 v17, v19
	v_cvt_pk_bf16_f32 v0, v0, v1
	v_cvt_pk_bf16_f32 v1, v2, v3
	v_cvt_pk_bf16_f32 v2, v4, v5
	v_cvt_pk_bf16_f32 v3, v6, v7
	global_store_dwordx4 v[172:173], v[32:35], off offset:96
	global_store_dwordx4 v[172:173], v[16:19], off offset:128
	v_permlane32_swap_b32_e32 v49, v51
	s_nop 0
	v_cvt_pk_bf16_f32 v16, v24, v25
	v_cvt_pk_bf16_f32 v17, v26, v27
	v_cvt_pk_bf16_f32 v18, v28, v29
	v_cvt_pk_bf16_f32 v19, v30, v31
	v_mfma_f32_32x32x16_bf16 v[32:47], v[120:123], v[0:3], 0
	v_permlane32_swap_b32_e32 v16, v18
	v_permlane32_swap_b32_e32 v17, v19
	global_store_dwordx4 v[172:173], v[16:19], off offset:160
	global_store_dwordx4 v[172:173], v[48:51], off
	v_cndmask_b32_e64 v4, 0, v128, s[4:5]
	v_mfma_f32_32x32x16_bf16 v[16:31], v[116:119], v[0:3], 0
	v_cvt_pk_bf16_f32 v48, v56, v57
	v_cvt_pk_bf16_f32 v49, v58, v59
	v_cvt_pk_bf16_f32 v50, v60, v61
	v_cvt_pk_bf16_f32 v51, v62, v63
	s_nop 0
	v_permlane32_swap_b32_e32 v48, v50
	v_permlane32_swap_b32_e32 v49, v51
	global_store_dwordx4 v[172:173], v[48:51], off offset:32
	v_cndmask_b32_e64 v5, 0, v129, s[4:5]
	v_cndmask_b32_e64 v6, 0, v130, s[4:5]
	v_cndmask_b32_e64 v7, 0, v131, s[4:5]
	v_cndmask_b32_e64 v50, 0, v132, s[4:5]
	v_cndmask_b32_e64 v51, 0, v133, s[4:5]
	v_cndmask_b32_e64 v56, 0, v134, s[4:5]
	v_cndmask_b32_e64 v57, 0, v135, s[4:5]
	v_cvt_pk_bf16_f32 v48, v4, v5
	v_cvt_pk_bf16_f32 v49, v6, v7
	v_cvt_pk_bf16_f32 v50, v50, v51
	v_cvt_pk_bf16_f32 v51, v56, v57
	v_permlane32_swap_b32_e32 v52, v54
	s_nop 0
	v_mfma_f32_32x32x16_bf16 v[32:47], v[112:115], v[48:51], v[32:47]
	v_permlane32_swap_b32_e32 v53, v55
	global_store_dwordx4 v[172:173], v[52:55], off offset:192
	v_cndmask_b32_e64 v4, 0, v136, s[4:5]
	v_cndmask_b32_e64 v5, 0, v137, s[4:5]
	v_cndmask_b32_e64 v6, 0, v138, s[4:5]
	v_cndmask_b32_e64 v7, 0, v139, s[4:5]
	v_mfma_f32_32x32x16_bf16 v[16:31], v[108:111], v[48:51], v[16:31]
	v_cndmask_b32_e64 v54, 0, v140, s[4:5]
	v_cndmask_b32_e64 v55, 0, v141, s[4:5]
	v_cndmask_b32_e64 v56, 0, v142, s[4:5]
	v_cndmask_b32_e64 v57, 0, v143, s[4:5]
	v_cvt_pk_bf16_f32 v52, v4, v5
	v_cvt_pk_bf16_f32 v53, v6, v7
	v_cvt_pk_bf16_f32 v54, v54, v55
	v_cvt_pk_bf16_f32 v55, v56, v57
	v_cvt_pk_bf16_f32 v4, v8, v9
	v_cvt_pk_bf16_f32 v5, v10, v11
	v_mfma_f32_32x32x16_bf16 v[32:47], v[104:107], v[52:55], v[32:47]
	v_cndmask_b32_e64 v6, 0, v156, s[4:5]
	v_cndmask_b32_e64 v7, 0, v157, s[4:5]
	v_cndmask_b32_e64 v8, 0, v158, s[4:5]
	v_cndmask_b32_e64 v9, 0, v159, s[4:5]
	v_cndmask_b32_e64 v10, 0, v152, s[4:5]
	v_cndmask_b32_e64 v11, 0, v153, s[4:5]
	v_cndmask_b32_e64 v59, 0, v154, s[4:5]
	v_mfma_f32_32x32x16_bf16 v[16:31], v[100:103], v[52:55], v[16:31]
	v_cndmask_b32_e64 v60, 0, v155, s[4:5]
	v_cvt_pk_bf16_f32 v56, v6, v7
	v_cvt_pk_bf16_f32 v57, v8, v9
	v_cvt_pk_bf16_f32 v58, v10, v11
	v_cvt_pk_bf16_f32 v59, v59, v60
	v_cvt_pk_bf16_f32 v6, v12, v13
	v_cvt_pk_bf16_f32 v7, v14, v15
	v_mfma_f32_32x32x16_bf16 v[32:47], v[96:99], v[56:59], v[32:47]
	v_permlane32_swap_b32_e32 v4, v6
	v_permlane32_swap_b32_e32 v5, v7
	global_store_dwordx4 v[172:173], v[4:7], off offset:224
	v_mfma_f32_32x32x16_bf16 v[16:31], v[92:95], v[56:59], v[16:31]
	s_nop 7
	v_cvt_pk_bf16_f32 v4, v32, v33
	v_cvt_pk_bf16_f32 v5, v34, v35
	v_cvt_pk_bf16_f32 v6, v36, v37
	v_cvt_pk_bf16_f32 v7, v38, v39
	s_nop 0
	v_permlane32_swap_b32_e32 v4, v6
	v_permlane32_swap_b32_e32 v5, v7
	s_and_saveexec_b64 s[66:67], s[4:5]
	s_cbranch_execz .LBB0_414
	v_add_co_u32_e32 v8, vcc, 0x8000, v208
	s_nop 1
	v_addc_co_u32_e32 v9, vcc, 0, v209, vcc
	global_store_dwordx4 v[8:9], v[4:7], off
